# M-path trim + saddr LDS-DMA (no VALU in load segs) + move A-h0 DMA pair from SP2 to next SP1 load segment
# speedup vs baseline: 1.0064x; 1.0064x over previous
; #define PG8_STAGE(bufoff, gbase, voff) do { _Pragma("unroll") for (int _i = 0; _i < 2; ++_i) \
;         __builtin_amdgcn_global_load_lds((const unsigned*)((const char*)(gbase) + (voff)[_i]), (PG8_LAS unsigned*)(lds + (bufoff) + ldsw + _i * 8192), 16, 0, 0); } while (0)
; #define PG8_LDA(dst, b, h) do { _Pragma("unroll") for (int m = 0; m < 4; ++m) _Pragma("unroll") for (int k = 0; k < 2; ++k) dst[m][k] = *(const PG8_LAS bf16x8*)(lds + PG8_SA(b, h) + aoff + m * 2048 + k * 1024); } while (0)
; #define PG8_LDB(dst, b, h) do { _Pragma("unroll") for (int n = 0; n < 2; ++n) _Pragma("unroll") for (int k = 0; k < 2; ++k) dst[n][k] = *(const PG8_LAS bf16x8*)(lds + PG8_SB(b, h) + boff + n * 2048 + k * 1024); } while (0)
; #define PG8_MMA(ai, bj, At, Bt) do { __builtin_amdgcn_s_setprio(1); _Pragma("unroll") for (int m = 0; m < 4; ++m) _Pragma("unroll") for (int n = 0; n < 2; ++n) _Pragma("unroll") for (int k = 0; k < 2; ++k) \
;         acc[ai][bj][m][n] = __builtin_amdgcn_mfma_f32_16x16x32_bf16(Bt[n][k], At[m][k], acc[ai][bj][m][n], 0, 0, 0); __builtin_amdgcn_s_setprio(0); } while (0)
; #define PG8_WAIT_V(n) asm volatile("s_waitcnt vmcnt(" #n ")" ::: "memory")
; #define PG8_WAIT_L(n) asm volatile("s_waitcnt lgkmcnt(" #n ")" ::: "memory")
; #define PG8_BAR __builtin_amdgcn_s_barrier()
; #define PG8_SCHED __builtin_amdgcn_sched_barrier(0)
; template <class Epi, class Sched, bool ALIGN_EPI = false, bool SP2 = false>
; __device__ __forceinline__ void gemm_phase(PG8_LAS unsigned char* lds, const Gemm g, const Sched& S, const Epi& E) {
;     ...
;             PG8_LDB(B0, 0, 0); PG8_LDB(B1, 0, 1); PG8_SCHED; PG8_LDA(At, 0, 0); PG8_STAGE(PG8_SA(1, 1), a1 + hstepA, voffA);
;             PG8_WAIT_V(8); PG8_WAIT_L(0); PG8_BAR; PG8_MMA(0, 0, At, B0); PG8_MMA(0, 1, At, B1); PG8_BAR; PG8_SCHED;
;             PG8_LDA(At, 0, 1); PG8_STAGE(PG8_SB(0, 0), b2, voffB); PG8_STAGE(PG8_SB(0, 1), b2 + hstepB, voffB); PG8_STAGE(PG8_SA(0, 0), a2, voffA);
;             PG8_WAIT_V(8); PG8_WAIT_L(0); PG8_BAR; PG8_MMA(1, 0, At, B0); PG8_MMA(1, 1, At, B1); PG8_BAR; PG8_SCHED;
.LBB0_277:
	ds_read_b128 v[136:139], v129
	ds_read_b128 v[146:149], v129 offset:1024
	ds_read_b128 v[150:153], v129 offset:2048
	ds_read_b128 v[154:157], v129 offset:3072
	ds_read_b128 v[158:161], v143
	ds_read_b128 v[162:165], v143 offset:1024
	ds_read_b128 v[166:169], v143 offset:2048
	ds_read_b128 v[170:173], v143 offset:3072
	s_add_u32 s42, s40, 0xfff80080
	s_addc_u32 s43, s41, -1
	s_cmp_eq_u32 s56, 28
	s_cselect_b32 s45, s29, s43
	s_cselect_b32 s44, s52, s42
	s_cselect_b32 s43, s27, s55
	s_cselect_b32 s42, s53, s54
	s_add_i32 m0, s10, 0xc000
	ds_read_b128 v[174:177], v144
	ds_read_b128 v[178:181], v144 offset:1024
	ds_read_b128 v[182:185], v144 offset:2048
	ds_read_b128 v[204:207], v144 offset:3072
	ds_read_b128 v[208:211], v144 offset:4096
	ds_read_b128 v[212:215], v144 offset:5120
	ds_read_b128 v[216:219], v144 offset:6144
	ds_read_b128 v[220:223], v144 offset:7168
	global_load_lds_dwordx4 v132, s[40:41]
	s_add_i32 m0, s10, 0xe000
	s_nop 0
	global_load_lds_dwordx4 v134, s[40:41]
	s_waitcnt vmcnt(8)
	s_waitcnt lgkmcnt(0)
	s_setprio 1
	s_barrier
	v_mfma_f32_16x16x32_bf16 v[124:127], v[136:139], v[174:177], v[124:127]
	v_mfma_f32_16x16x32_bf16 v[120:123], v[150:153], v[174:177], v[120:123]
	v_mfma_f32_16x16x32_bf16 v[108:111], v[136:139], v[182:185], v[108:111]
	v_mfma_f32_16x16x32_bf16 v[104:107], v[150:153], v[182:185], v[104:107]
	v_mfma_f32_16x16x32_bf16 v[92:95], v[136:139], v[208:211], v[92:95]
	v_mfma_f32_16x16x32_bf16 v[88:91], v[150:153], v[208:211], v[88:91]
	v_mfma_f32_16x16x32_bf16 v[76:79], v[136:139], v[216:219], v[76:79]
	v_mfma_f32_16x16x32_bf16 v[72:75], v[150:153], v[216:219], v[72:75]
	v_mfma_f32_16x16x32_bf16 v[124:127], v[146:149], v[178:181], v[124:127]
	v_mfma_f32_16x16x32_bf16 v[120:123], v[154:157], v[178:181], v[120:123]
	v_mfma_f32_16x16x32_bf16 v[108:111], v[146:149], v[204:207], v[108:111]
	v_mfma_f32_16x16x32_bf16 v[104:107], v[154:157], v[204:207], v[104:107]
	v_mfma_f32_16x16x32_bf16 v[92:95], v[146:149], v[212:215], v[92:95]
	v_mfma_f32_16x16x32_bf16 v[88:91], v[154:157], v[212:215], v[88:91]
	v_mfma_f32_16x16x32_bf16 v[76:79], v[146:149], v[220:223], v[76:79]
	v_mfma_f32_16x16x32_bf16 v[72:75], v[154:157], v[220:223], v[72:75]
	v_mfma_f32_16x16x32_bf16 v[116:119], v[158:161], v[174:177], v[116:119]
	v_mfma_f32_16x16x32_bf16 v[112:115], v[166:169], v[174:177], v[112:115]
	v_mfma_f32_16x16x32_bf16 v[100:103], v[158:161], v[182:185], v[100:103]
	v_mfma_f32_16x16x32_bf16 v[96:99], v[166:169], v[182:185], v[96:99]
	v_mfma_f32_16x16x32_bf16 v[84:87], v[158:161], v[208:211], v[84:87]
	v_mfma_f32_16x16x32_bf16 v[80:83], v[166:169], v[208:211], v[80:83]
	v_mfma_f32_16x16x32_bf16 v[68:71], v[158:161], v[216:219], v[68:71]
	v_mfma_f32_16x16x32_bf16 v[64:67], v[166:169], v[216:219], v[64:67]
	v_mfma_f32_16x16x32_bf16 v[116:119], v[162:165], v[178:181], v[116:119]
	v_mfma_f32_16x16x32_bf16 v[112:115], v[170:173], v[178:181], v[112:115]
	v_mfma_f32_16x16x32_bf16 v[100:103], v[162:165], v[204:207], v[100:103]
	v_mfma_f32_16x16x32_bf16 v[96:99], v[170:173], v[204:207], v[96:99]
	v_mfma_f32_16x16x32_bf16 v[84:87], v[162:165], v[212:215], v[84:87]
	v_mfma_f32_16x16x32_bf16 v[80:83], v[170:173], v[212:215], v[80:83]
	v_mfma_f32_16x16x32_bf16 v[68:71], v[162:165], v[220:223], v[68:71]
	v_mfma_f32_16x16x32_bf16 v[64:67], v[170:173], v[220:223], v[64:67]
	s_barrier
	s_add_u32 s98, s44, s20
	s_addc_u32 s99, s45, s21
	s_setprio 0
	s_add_i32 s57, s49, s2
	s_mov_b32 m0, s57
	ds_read_b128 v[174:177], v144 offset:16384
	ds_read_b128 v[178:181], v144 offset:17408
	ds_read_b128 v[182:185], v144 offset:18432
	ds_read_b128 v[204:207], v144 offset:19456
	ds_read_b128 v[208:211], v144 offset:20480
	ds_read_b128 v[212:215], v144 offset:21504
	ds_read_b128 v[216:219], v144 offset:22528
	ds_read_b128 v[220:223], v144 offset:23552
	global_load_lds_dwordx4 v194, s[42:43]
	s_add_i32 m0, s57, 0x2000
	s_add_u32 s58, s42, 0x4000
	s_addc_u32 s59, s43, 0
	s_add_i32 s57, s50, s2
	global_load_lds_dwordx4 v198, s[42:43]
	s_mov_b32 m0, s57
	s_nop 0
	global_load_lds_dwordx4 v194, s[58:59]
	s_add_i32 m0, s57, 0x2000
	s_nop 0
	global_load_lds_dwordx4 v198, s[58:59]
	s_waitcnt vmcnt(6)
	s_waitcnt lgkmcnt(0)
	s_setprio 1
	s_barrier
	v_mfma_f32_16x16x32_bf16 v[60:63], v[136:139], v[174:177], v[60:63]
	v_mfma_f32_16x16x32_bf16 v[56:59], v[150:153], v[174:177], v[56:59]
	v_mfma_f32_16x16x32_bf16 v[44:47], v[136:139], v[182:185], v[44:47]
	v_mfma_f32_16x16x32_bf16 v[40:43], v[150:153], v[182:185], v[40:43]
	v_mfma_f32_16x16x32_bf16 v[28:31], v[136:139], v[208:211], v[28:31]
	v_mfma_f32_16x16x32_bf16 v[24:27], v[150:153], v[208:211], v[24:27]
	v_mfma_f32_16x16x32_bf16 v[12:15], v[136:139], v[216:219], v[12:15]
	v_mfma_f32_16x16x32_bf16 v[8:11], v[150:153], v[216:219], v[8:11]
	v_mfma_f32_16x16x32_bf16 v[60:63], v[146:149], v[178:181], v[60:63]
	v_mfma_f32_16x16x32_bf16 v[56:59], v[154:157], v[178:181], v[56:59]
	v_mfma_f32_16x16x32_bf16 v[44:47], v[146:149], v[204:207], v[44:47]
	v_mfma_f32_16x16x32_bf16 v[40:43], v[154:157], v[204:207], v[40:43]
	v_mfma_f32_16x16x32_bf16 v[28:31], v[146:149], v[212:215], v[28:31]
	v_mfma_f32_16x16x32_bf16 v[24:27], v[154:157], v[212:215], v[24:27]
	v_mfma_f32_16x16x32_bf16 v[12:15], v[146:149], v[220:223], v[12:15]
	v_mfma_f32_16x16x32_bf16 v[8:11], v[154:157], v[220:223], v[8:11]
	v_mfma_f32_16x16x32_bf16 v[52:55], v[158:161], v[174:177], v[52:55]
	v_mfma_f32_16x16x32_bf16 v[48:51], v[166:169], v[174:177], v[48:51]
	v_mfma_f32_16x16x32_bf16 v[36:39], v[158:161], v[182:185], v[36:39]
	v_mfma_f32_16x16x32_bf16 v[32:35], v[166:169], v[182:185], v[32:35]
	v_mfma_f32_16x16x32_bf16 v[20:23], v[158:161], v[208:211], v[20:23]
	v_mfma_f32_16x16x32_bf16 v[16:19], v[166:169], v[208:211], v[16:19]
	v_mfma_f32_16x16x32_bf16 v[4:7], v[158:161], v[216:219], v[4:7]
	v_mfma_f32_16x16x32_bf16 v[0:3], v[166:169], v[216:219], v[0:3]
	v_mfma_f32_16x16x32_bf16 v[52:55], v[162:165], v[178:181], v[52:55]
	v_mfma_f32_16x16x32_bf16 v[48:51], v[170:173], v[178:181], v[48:51]
	v_mfma_f32_16x16x32_bf16 v[36:39], v[162:165], v[204:207], v[36:39]
	v_mfma_f32_16x16x32_bf16 v[32:35], v[170:173], v[204:207], v[32:35]
	v_mfma_f32_16x16x32_bf16 v[20:23], v[162:165], v[212:215], v[20:23]
	v_mfma_f32_16x16x32_bf16 v[16:19], v[170:173], v[212:215], v[16:19]
	v_mfma_f32_16x16x32_bf16 v[4:7], v[162:165], v[220:223], v[4:7]
	v_mfma_f32_16x16x32_bf16 v[0:3], v[170:173], v[220:223], v[0:3]
	s_barrier
; #define PG8_STAGE(bufoff, gbase, voff) do { _Pragma("unroll") for (int _i = 0; _i < 2; ++_i) \
;         __builtin_amdgcn_global_load_lds((const unsigned*)((const char*)(gbase) + (voff)[_i]), (PG8_LAS unsigned*)(lds + (bufoff) + ldsw + _i * 8192), 16, 0, 0); } while (0)
; #define PG8_LDA(dst, b, h) do { _Pragma("unroll") for (int m = 0; m < 4; ++m) _Pragma("unroll") for (int k = 0; k < 2; ++k) dst[m][k] = *(const PG8_LAS bf16x8*)(lds + PG8_SA(b, h) + aoff + m * 2048 + k * 1024); } while (0)
; #define PG8_LDB(dst, b, h) do { _Pragma("unroll") for (int n = 0; n < 2; ++n) _Pragma("unroll") for (int k = 0; k < 2; ++k) dst[n][k] = *(const PG8_LAS bf16x8*)(lds + PG8_SB(b, h) + boff + n * 2048 + k * 1024); } while (0)
; #define PG8_MMA(ai, bj, At, Bt) do { __builtin_amdgcn_s_setprio(1); _Pragma("unroll") for (int m = 0; m < 4; ++m) _Pragma("unroll") for (int n = 0; n < 2; ++n) _Pragma("unroll") for (int k = 0; k < 2; ++k) \
;         acc[ai][bj][m][n] = __builtin_amdgcn_mfma_f32_16x16x32_bf16(Bt[n][k], At[m][k], acc[ai][bj][m][n], 0, 0, 0); __builtin_amdgcn_s_setprio(0); } while (0)
; #define PG8_WAIT_V(n) asm volatile("s_waitcnt vmcnt(" #n ")" ::: "memory")
; #define PG8_WAIT_L(n) asm volatile("s_waitcnt lgkmcnt(" #n ")" ::: "memory")
; #define PG8_BAR __builtin_amdgcn_s_barrier()
; template <class Epi, class Sched, bool ALIGN_EPI = false, bool SP2 = false>
; __device__ __forceinline__ void gemm_phase(PG8_LAS unsigned char* lds, const Gemm g, const Sched& S, const Epi& E) {
;     ...
;         for (int t = 0; t < nt; t += 2) {
;             const bool last = (t == nt - 2);
;             const char* a1 = cA + (size_t)(t + 1) * kstepA;
;             const char* a2 = last ? nA : cA + (size_t)(t + 2) * kstepA; const char* b2 = last ? nB : cB + (size_t)(t + 2) * kstepB;
;             const char* a3 = a2 + kstepA; const char* b3 = b2 + kstepB;
;     ...
;             PG8_LDB(B0, 1, 0); PG8_LDB(B1, 1, 1); PG8_SCHED; PG8_LDA(At, 1, 0); PG8_STAGE(PG8_SA(0, 1), a2 + hstepA, voffA);
;             PG8_WAIT_V(8); PG8_WAIT_L(0); PG8_BAR; PG8_MMA(0, 0, At, B0); PG8_MMA(0, 1, At, B1); PG8_BAR; PG8_SCHED;
;             PG8_LDA(At, 1, 1); PG8_STAGE(PG8_SB(1, 0), b3, voffB); PG8_STAGE(PG8_SB(1, 1), b3 + hstepB, voffB); PG8_STAGE(PG8_SA(1, 0), a3, voffA);
;             PG8_WAIT_V(8); PG8_WAIT_L(0); PG8_BAR; PG8_MMA(1, 0, At, B0); PG8_MMA(1, 1, At, B1); PG8_BAR; PG8_SCHED;
	s_setprio 0
	s_add_i32 s57, 0, 0x18000
	s_add_i32 s58, 0, 0x1c000
	v_add_u32_e32 v154, s57, v142
	v_add_u32_e32 v170, s58, v142
	ds_read_b128 v[136:139], v154
	ds_read_b128 v[146:149], v154 offset:1024
	ds_read_b128 v[150:153], v154 offset:2048
	ds_read_b128 v[154:157], v154 offset:3072
	ds_read_b128 v[158:161], v170
	ds_read_b128 v[162:165], v170 offset:1024
	ds_read_b128 v[166:169], v170 offset:2048
	ds_read_b128 v[170:173], v170 offset:3072
	s_mov_b32 m0, s10
	s_nop 0
	global_load_lds_dwordx4 v192, s[44:45]
	s_mov_b32 m0, s12
	s_nop 0
	global_load_lds_dwordx4 v196, s[44:45]
	s_add_u32 s44, s44, 0x80000
	s_addc_u32 s45, s45, 0
	s_mov_b32 m0, s13
	ds_read_b128 v[174:177], v144 offset:32768
	ds_read_b128 v[178:181], v144 offset:33792
	ds_read_b128 v[182:185], v144 offset:34816
	ds_read_b128 v[204:207], v144 offset:35840
	ds_read_b128 v[208:211], v144 offset:36864
	ds_read_b128 v[212:215], v144 offset:37888
	ds_read_b128 v[216:219], v144 offset:38912
	ds_read_b128 v[220:223], v144 offset:39936
	global_load_lds_dwordx4 v192, s[44:45]
	s_mov_b32 m0, s14
	s_nop 0
	global_load_lds_dwordx4 v196, s[44:45]
	s_waitcnt vmcnt(8)
	s_waitcnt lgkmcnt(0)
	s_setprio 1
	s_barrier
	v_mfma_f32_16x16x32_bf16 v[124:127], v[136:139], v[174:177], v[124:127]
	v_mfma_f32_16x16x32_bf16 v[120:123], v[150:153], v[174:177], v[120:123]
	v_mfma_f32_16x16x32_bf16 v[108:111], v[136:139], v[182:185], v[108:111]
	v_mfma_f32_16x16x32_bf16 v[104:107], v[150:153], v[182:185], v[104:107]
	v_mfma_f32_16x16x32_bf16 v[92:95], v[136:139], v[208:211], v[92:95]
	v_mfma_f32_16x16x32_bf16 v[88:91], v[150:153], v[208:211], v[88:91]
	v_mfma_f32_16x16x32_bf16 v[76:79], v[136:139], v[216:219], v[76:79]
	v_mfma_f32_16x16x32_bf16 v[72:75], v[150:153], v[216:219], v[72:75]
	v_mfma_f32_16x16x32_bf16 v[124:127], v[146:149], v[178:181], v[124:127]
	v_mfma_f32_16x16x32_bf16 v[120:123], v[154:157], v[178:181], v[120:123]
	v_mfma_f32_16x16x32_bf16 v[108:111], v[146:149], v[204:207], v[108:111]
	v_mfma_f32_16x16x32_bf16 v[104:107], v[154:157], v[204:207], v[104:107]
	v_mfma_f32_16x16x32_bf16 v[92:95], v[146:149], v[212:215], v[92:95]
	v_mfma_f32_16x16x32_bf16 v[88:91], v[154:157], v[212:215], v[88:91]
	v_mfma_f32_16x16x32_bf16 v[76:79], v[146:149], v[220:223], v[76:79]
	v_mfma_f32_16x16x32_bf16 v[72:75], v[154:157], v[220:223], v[72:75]
	v_mfma_f32_16x16x32_bf16 v[116:119], v[158:161], v[174:177], v[116:119]
	v_mfma_f32_16x16x32_bf16 v[112:115], v[166:169], v[174:177], v[112:115]
	v_mfma_f32_16x16x32_bf16 v[100:103], v[158:161], v[182:185], v[100:103]
	v_mfma_f32_16x16x32_bf16 v[96:99], v[166:169], v[182:185], v[96:99]
	v_mfma_f32_16x16x32_bf16 v[84:87], v[158:161], v[208:211], v[84:87]
	v_mfma_f32_16x16x32_bf16 v[80:83], v[166:169], v[208:211], v[80:83]
	v_mfma_f32_16x16x32_bf16 v[68:71], v[158:161], v[216:219], v[68:71]
	v_mfma_f32_16x16x32_bf16 v[64:67], v[166:169], v[216:219], v[64:67]
	v_mfma_f32_16x16x32_bf16 v[116:119], v[162:165], v[178:181], v[116:119]
	v_mfma_f32_16x16x32_bf16 v[112:115], v[170:173], v[178:181], v[112:115]
	v_mfma_f32_16x16x32_bf16 v[100:103], v[162:165], v[204:207], v[100:103]
	v_mfma_f32_16x16x32_bf16 v[96:99], v[170:173], v[204:207], v[96:99]
	v_mfma_f32_16x16x32_bf16 v[84:87], v[162:165], v[212:215], v[84:87]
	v_mfma_f32_16x16x32_bf16 v[80:83], v[170:173], v[212:215], v[80:83]
	v_mfma_f32_16x16x32_bf16 v[68:71], v[162:165], v[220:223], v[68:71]
	v_mfma_f32_16x16x32_bf16 v[64:67], v[170:173], v[220:223], v[64:67]
	s_barrier
	s_setprio 0
	s_add_u32 s44, s42, 0x8000
	s_addc_u32 s45, s43, 0
	s_add_i32 s57, s57, s2
	s_mov_b32 m0, s57
	ds_read_b128 v[174:177], v144 offset:49152
	ds_read_b128 v[178:181], v144 offset:50176
	ds_read_b128 v[182:185], v144 offset:51200
	ds_read_b128 v[204:207], v144 offset:52224
	ds_read_b128 v[208:211], v144 offset:53248
	ds_read_b128 v[212:215], v144 offset:54272
	ds_read_b128 v[216:219], v144 offset:55296
	ds_read_b128 v[220:223], v144 offset:56320
	global_load_lds_dwordx4 v194, s[44:45]
	s_add_i32 m0, s57, 0x2000
	s_add_u32 s42, s42, 0xc000
	s_addc_u32 s43, s43, 0
	global_load_lds_dwordx4 v198, s[44:45]
	s_add_i32 s44, s58, s2
	s_mov_b32 m0, s44
	s_nop 0
	global_load_lds_dwordx4 v194, s[42:43]
	s_add_i32 m0, s44, 0x2000
	s_nop 0
	global_load_lds_dwordx4 v198, s[42:43]
	s_mov_b32 m0, s15
	s_nop 0
	global_load_lds_dwordx4 v192, s[98:99]
	s_mov_b32 m0, s47
	s_nop 0
	global_load_lds_dwordx4 v196, s[98:99]
	s_waitcnt vmcnt(8)
	s_waitcnt lgkmcnt(0)
	s_setprio 1
	s_barrier
	v_mfma_f32_16x16x32_bf16 v[60:63], v[136:139], v[174:177], v[60:63]
	v_mfma_f32_16x16x32_bf16 v[56:59], v[150:153], v[174:177], v[56:59]
	v_mfma_f32_16x16x32_bf16 v[44:47], v[136:139], v[182:185], v[44:47]
	v_mfma_f32_16x16x32_bf16 v[40:43], v[150:153], v[182:185], v[40:43]
	v_mfma_f32_16x16x32_bf16 v[28:31], v[136:139], v[208:211], v[28:31]
	v_mfma_f32_16x16x32_bf16 v[24:27], v[150:153], v[208:211], v[24:27]
	v_mfma_f32_16x16x32_bf16 v[12:15], v[136:139], v[216:219], v[12:15]
	v_mfma_f32_16x16x32_bf16 v[8:11], v[150:153], v[216:219], v[8:11]
	v_mfma_f32_16x16x32_bf16 v[60:63], v[146:149], v[178:181], v[60:63]
	v_mfma_f32_16x16x32_bf16 v[56:59], v[154:157], v[178:181], v[56:59]
	v_mfma_f32_16x16x32_bf16 v[44:47], v[146:149], v[204:207], v[44:47]
	v_mfma_f32_16x16x32_bf16 v[40:43], v[154:157], v[204:207], v[40:43]
	v_mfma_f32_16x16x32_bf16 v[28:31], v[146:149], v[212:215], v[28:31]
	v_mfma_f32_16x16x32_bf16 v[24:27], v[154:157], v[212:215], v[24:27]
	v_mfma_f32_16x16x32_bf16 v[12:15], v[146:149], v[220:223], v[12:15]
	v_mfma_f32_16x16x32_bf16 v[8:11], v[154:157], v[220:223], v[8:11]
	v_mfma_f32_16x16x32_bf16 v[52:55], v[158:161], v[174:177], v[52:55]
	v_mfma_f32_16x16x32_bf16 v[48:51], v[166:169], v[174:177], v[48:51]
	v_mfma_f32_16x16x32_bf16 v[36:39], v[158:161], v[182:185], v[36:39]
	v_mfma_f32_16x16x32_bf16 v[32:35], v[166:169], v[182:185], v[32:35]
	v_mfma_f32_16x16x32_bf16 v[20:23], v[158:161], v[208:211], v[20:23]
	v_mfma_f32_16x16x32_bf16 v[16:19], v[166:169], v[208:211], v[16:19]
	v_mfma_f32_16x16x32_bf16 v[4:7], v[158:161], v[216:219], v[4:7]
	v_mfma_f32_16x16x32_bf16 v[0:3], v[166:169], v[216:219], v[0:3]
	v_mfma_f32_16x16x32_bf16 v[52:55], v[162:165], v[178:181], v[52:55]
	v_mfma_f32_16x16x32_bf16 v[48:51], v[170:173], v[178:181], v[48:51]
	v_mfma_f32_16x16x32_bf16 v[36:39], v[162:165], v[204:207], v[36:39]
	v_mfma_f32_16x16x32_bf16 v[32:35], v[170:173], v[204:207], v[32:35]
	v_mfma_f32_16x16x32_bf16 v[20:23], v[162:165], v[212:215], v[20:23]
	v_mfma_f32_16x16x32_bf16 v[16:19], v[170:173], v[212:215], v[16:19]
	v_mfma_f32_16x16x32_bf16 v[4:7], v[162:165], v[220:223], v[4:7]
	v_mfma_f32_16x16x32_bf16 v[0:3], v[170:173], v[220:223], v[0:3]
	s_barrier
	s_setprio 0
	s_add_i32 s56, s56, 2
	s_add_u32 s54, s54, 0x10000
	s_addc_u32 s55, s55, 0
	s_add_u32 s40, s40, 0x100
	s_addc_u32 s41, s41, 0
	s_cmp_gt_u32 s56, 29
	s_cbranch_scc0 .LBB0_277
	s_and_b64 vcc, exec, s[24:25]
	s_cbranch_vccz .LBB0_280
	s_barrier

; #define PG8_STAGE(bufoff, gbase, voff) do { _Pragma("unroll") for (int _i = 0; _i < 2; ++_i) \
;         __builtin_amdgcn_global_load_lds((const unsigned*)((const char*)(gbase) + (voff)[_i]), (PG8_LAS unsigned*)(lds + (bufoff) + ldsw + _i * 8192), 16, 0, 0); } while (0)
; #define PG8_LDA(dst, b, h) do { _Pragma("unroll") for (int m = 0; m < 4; ++m) _Pragma("unroll") for (int k = 0; k < 2; ++k) dst[m][k] = *(const PG8_LAS bf16x8*)(lds + PG8_SA(b, h) + aoff + m * 2048 + k * 1024); } while (0)
; #define PG8_LDB(dst, b, h) do { _Pragma("unroll") for (int n = 0; n < 2; ++n) _Pragma("unroll") for (int k = 0; k < 2; ++k) dst[n][k] = *(const PG8_LAS bf16x8*)(lds + PG8_SB(b, h) + boff + n * 2048 + k * 1024); } while (0)
; #define PG8_MMA(ai, bj, At, Bt) do { __builtin_amdgcn_s_setprio(1); _Pragma("unroll") for (int m = 0; m < 4; ++m) _Pragma("unroll") for (int n = 0; n < 2; ++n) _Pragma("unroll") for (int k = 0; k < 2; ++k) \
;         acc[ai][bj][m][n] = __builtin_amdgcn_mfma_f32_16x16x32_bf16(Bt[n][k], At[m][k], acc[ai][bj][m][n], 0, 0, 0); __builtin_amdgcn_s_setprio(0); } while (0)
; #define PG8_WAIT_V(n) asm volatile("s_waitcnt vmcnt(" #n ")" ::: "memory")
; #define PG8_WAIT_L(n) asm volatile("s_waitcnt lgkmcnt(" #n ")" ::: "memory")
; #define PG8_BAR __builtin_amdgcn_s_barrier()
; #define PG8_SCHED __builtin_amdgcn_sched_barrier(0)
; template <class Epi, class Sched, bool ALIGN_EPI = false, bool SP2 = false>
; __device__ __forceinline__ void gemm_phase(PG8_LAS unsigned char* lds, const Gemm g, const Sched& S, const Epi& E) {
;     ...
;             PG8_LDB(B0, 0, 0); PG8_LDB(B1, 0, 1); PG8_SCHED; PG8_LDA(At, 0, 0); PG8_STAGE(PG8_SA(1, 1), a1 + hstepA, voffA);
;             PG8_WAIT_V(8); PG8_WAIT_L(0); PG8_BAR; PG8_MMA(0, 0, At, B0); PG8_MMA(0, 1, At, B1); PG8_BAR; PG8_SCHED;
;             PG8_LDA(At, 0, 1); PG8_STAGE(PG8_SB(0, 0), b2, voffB); PG8_STAGE(PG8_SB(0, 1), b2 + hstepB, voffB); PG8_STAGE(PG8_SA(0, 0), a2, voffA);
;             PG8_WAIT_V(8); PG8_WAIT_L(0); PG8_BAR; PG8_MMA(1, 0, At, B0); PG8_MMA(1, 1, At, B1); PG8_BAR; PG8_SCHED;
.LBB0_360:
	ds_read_b128 v[140:143], v185
	ds_read_b128 v[144:147], v185 offset:1024
	ds_read_b128 v[148:151], v185 offset:2048
	ds_read_b128 v[152:155], v185 offset:3072
	ds_read_b128 v[156:159], v201
	ds_read_b128 v[160:163], v201 offset:1024
	ds_read_b128 v[164:167], v201 offset:2048
	ds_read_b128 v[168:171], v201 offset:3072
	s_add_i32 s57, s36, 2
	s_add_u32 s37, s34, 0x4000
	s_addc_u32 s38, s35, 0
	s_cmp_eq_u32 s27, s36
	s_cselect_b32 s40, s28, s37
	s_cselect_b32 s41, s29, s38
	s_cselect_b32 s38, s30, s55
	s_cselect_b32 s39, s31, s56
	s_add_u32 s36, s40, 0x8000
	s_addc_u32 s37, s41, 0
	s_add_i32 m0, s10, 0xc000
	ds_read_b128 v[172:175], v204
	ds_read_b128 v[176:179], v204 offset:1024
	ds_read_b128 v[206:209], v204 offset:2048
	ds_read_b128 v[210:213], v204 offset:3072
	ds_read_b128 v[214:217], v204 offset:4096
	ds_read_b128 v[218:221], v204 offset:5120
	ds_read_b128 v[222:225], v204 offset:6144
	ds_read_b128 v[226:229], v204 offset:7168
	global_load_lds_dwordx4 v132, s[34:35]
	s_add_i32 m0, s10, 0xe000
	s_nop 0
	global_load_lds_dwordx4 v134, s[34:35]
	s_waitcnt vmcnt(8)
	s_waitcnt lgkmcnt(0)
	s_setprio 1
	s_barrier
	v_mfma_f32_16x16x32_bf16 v[124:127], v[140:143], v[172:175], v[124:127]
	v_mfma_f32_16x16x32_bf16 v[120:123], v[148:151], v[172:175], v[120:123]
	v_mfma_f32_16x16x32_bf16 v[108:111], v[140:143], v[206:209], v[108:111]
	v_mfma_f32_16x16x32_bf16 v[104:107], v[148:151], v[206:209], v[104:107]
	v_mfma_f32_16x16x32_bf16 v[92:95], v[140:143], v[214:217], v[92:95]
	v_mfma_f32_16x16x32_bf16 v[88:91], v[148:151], v[214:217], v[88:91]
	v_mfma_f32_16x16x32_bf16 v[76:79], v[140:143], v[222:225], v[76:79]
	v_mfma_f32_16x16x32_bf16 v[72:75], v[148:151], v[222:225], v[72:75]
	v_mfma_f32_16x16x32_bf16 v[124:127], v[144:147], v[176:179], v[124:127]
	v_mfma_f32_16x16x32_bf16 v[120:123], v[152:155], v[176:179], v[120:123]
	v_mfma_f32_16x16x32_bf16 v[108:111], v[144:147], v[210:213], v[108:111]
	v_mfma_f32_16x16x32_bf16 v[104:107], v[152:155], v[210:213], v[104:107]
	v_mfma_f32_16x16x32_bf16 v[92:95], v[144:147], v[218:221], v[92:95]
	v_mfma_f32_16x16x32_bf16 v[88:91], v[152:155], v[218:221], v[88:91]
	v_mfma_f32_16x16x32_bf16 v[76:79], v[144:147], v[226:229], v[76:79]
	v_mfma_f32_16x16x32_bf16 v[72:75], v[152:155], v[226:229], v[72:75]
	v_mfma_f32_16x16x32_bf16 v[116:119], v[156:159], v[172:175], v[116:119]
	v_mfma_f32_16x16x32_bf16 v[112:115], v[164:167], v[172:175], v[112:115]
	v_mfma_f32_16x16x32_bf16 v[100:103], v[156:159], v[206:209], v[100:103]
	v_mfma_f32_16x16x32_bf16 v[96:99], v[164:167], v[206:209], v[96:99]
	v_mfma_f32_16x16x32_bf16 v[84:87], v[156:159], v[214:217], v[84:87]
	v_mfma_f32_16x16x32_bf16 v[80:83], v[164:167], v[214:217], v[80:83]
	v_mfma_f32_16x16x32_bf16 v[68:71], v[156:159], v[222:225], v[68:71]
	v_mfma_f32_16x16x32_bf16 v[64:67], v[164:167], v[222:225], v[64:67]
	v_mfma_f32_16x16x32_bf16 v[116:119], v[160:163], v[176:179], v[116:119]
	v_mfma_f32_16x16x32_bf16 v[112:115], v[168:171], v[176:179], v[112:115]
	v_mfma_f32_16x16x32_bf16 v[100:103], v[160:163], v[210:213], v[100:103]
	v_mfma_f32_16x16x32_bf16 v[96:99], v[168:171], v[210:213], v[96:99]
	v_mfma_f32_16x16x32_bf16 v[84:87], v[160:163], v[218:221], v[84:87]
	v_mfma_f32_16x16x32_bf16 v[80:83], v[168:171], v[218:221], v[80:83]
	v_mfma_f32_16x16x32_bf16 v[68:71], v[160:163], v[226:229], v[68:71]
	v_mfma_f32_16x16x32_bf16 v[64:67], v[168:171], v[226:229], v[64:67]
	s_barrier
	s_setprio 0
	s_add_i32 s58, s44, s2
	s_mov_b32 m0, s58
	ds_read_b128 v[172:175], v204 offset:16384
	ds_read_b128 v[176:179], v204 offset:17408
	ds_read_b128 v[206:209], v204 offset:18432
	ds_read_b128 v[210:213], v204 offset:19456
	ds_read_b128 v[214:217], v204 offset:20480
	ds_read_b128 v[218:221], v204 offset:21504
	ds_read_b128 v[222:225], v204 offset:22528
	ds_read_b128 v[226:229], v204 offset:23552
	global_load_lds_dwordx4 v128, s[38:39]
	s_add_i32 m0, s58, 0x2000
	s_add_u32 s58, s38, 0x4000
	s_addc_u32 s59, s39, 0
	s_add_i32 s60, s45, s2
	global_load_lds_dwordx4 v130, s[38:39]
	s_mov_b32 m0, s60
	s_nop 0
	global_load_lds_dwordx4 v128, s[58:59]
	s_add_i32 m0, s60, 0x2000
	s_nop 0
	global_load_lds_dwordx4 v130, s[58:59]
	s_waitcnt vmcnt(6)
	s_waitcnt lgkmcnt(0)
	s_setprio 1
	s_barrier
	v_mfma_f32_16x16x32_bf16 v[60:63], v[140:143], v[172:175], v[60:63]
	v_mfma_f32_16x16x32_bf16 v[56:59], v[148:151], v[172:175], v[56:59]
	v_mfma_f32_16x16x32_bf16 v[44:47], v[140:143], v[206:209], v[44:47]
	v_mfma_f32_16x16x32_bf16 v[40:43], v[148:151], v[206:209], v[40:43]
	v_mfma_f32_16x16x32_bf16 v[28:31], v[140:143], v[214:217], v[28:31]
	v_mfma_f32_16x16x32_bf16 v[24:27], v[148:151], v[214:217], v[24:27]
	v_mfma_f32_16x16x32_bf16 v[12:15], v[140:143], v[222:225], v[12:15]
	v_mfma_f32_16x16x32_bf16 v[8:11], v[148:151], v[222:225], v[8:11]
	v_mfma_f32_16x16x32_bf16 v[60:63], v[144:147], v[176:179], v[60:63]
	v_mfma_f32_16x16x32_bf16 v[56:59], v[152:155], v[176:179], v[56:59]
	v_mfma_f32_16x16x32_bf16 v[44:47], v[144:147], v[210:213], v[44:47]
	v_mfma_f32_16x16x32_bf16 v[40:43], v[152:155], v[210:213], v[40:43]
	v_mfma_f32_16x16x32_bf16 v[28:31], v[144:147], v[218:221], v[28:31]
	v_mfma_f32_16x16x32_bf16 v[24:27], v[152:155], v[218:221], v[24:27]
	v_mfma_f32_16x16x32_bf16 v[12:15], v[144:147], v[226:229], v[12:15]
	v_mfma_f32_16x16x32_bf16 v[8:11], v[152:155], v[226:229], v[8:11]
	v_mfma_f32_16x16x32_bf16 v[52:55], v[156:159], v[172:175], v[52:55]
	v_mfma_f32_16x16x32_bf16 v[48:51], v[164:167], v[172:175], v[48:51]
	v_mfma_f32_16x16x32_bf16 v[36:39], v[156:159], v[206:209], v[36:39]
	v_mfma_f32_16x16x32_bf16 v[32:35], v[164:167], v[206:209], v[32:35]
	v_mfma_f32_16x16x32_bf16 v[20:23], v[156:159], v[214:217], v[20:23]
	v_mfma_f32_16x16x32_bf16 v[16:19], v[164:167], v[214:217], v[16:19]
	v_mfma_f32_16x16x32_bf16 v[4:7], v[156:159], v[222:225], v[4:7]
	v_mfma_f32_16x16x32_bf16 v[0:3], v[164:167], v[222:225], v[0:3]
	v_mfma_f32_16x16x32_bf16 v[52:55], v[160:163], v[176:179], v[52:55]
	v_mfma_f32_16x16x32_bf16 v[48:51], v[168:171], v[176:179], v[48:51]
	v_mfma_f32_16x16x32_bf16 v[36:39], v[160:163], v[210:213], v[36:39]
	v_mfma_f32_16x16x32_bf16 v[32:35], v[168:171], v[210:213], v[32:35]
	v_mfma_f32_16x16x32_bf16 v[20:23], v[160:163], v[218:221], v[20:23]
	v_mfma_f32_16x16x32_bf16 v[16:19], v[168:171], v[218:221], v[16:19]
	v_mfma_f32_16x16x32_bf16 v[4:7], v[160:163], v[226:229], v[4:7]
	v_mfma_f32_16x16x32_bf16 v[0:3], v[168:171], v[226:229], v[0:3]
	s_barrier
; #define PG8_STAGE(bufoff, gbase, voff) do { _Pragma("unroll") for (int _i = 0; _i < 2; ++_i) \
;         __builtin_amdgcn_global_load_lds((const unsigned*)((const char*)(gbase) + (voff)[_i]), (PG8_LAS unsigned*)(lds + (bufoff) + ldsw + _i * 8192), 16, 0, 0); } while (0)
; #define PG8_LDA(dst, b, h) do { _Pragma("unroll") for (int m = 0; m < 4; ++m) _Pragma("unroll") for (int k = 0; k < 2; ++k) dst[m][k] = *(const PG8_LAS bf16x8*)(lds + PG8_SA(b, h) + aoff + m * 2048 + k * 1024); } while (0)
; #define PG8_LDB(dst, b, h) do { _Pragma("unroll") for (int n = 0; n < 2; ++n) _Pragma("unroll") for (int k = 0; k < 2; ++k) dst[n][k] = *(const PG8_LAS bf16x8*)(lds + PG8_SB(b, h) + boff + n * 2048 + k * 1024); } while (0)
; #define PG8_MMA(ai, bj, At, Bt) do { __builtin_amdgcn_s_setprio(1); _Pragma("unroll") for (int m = 0; m < 4; ++m) _Pragma("unroll") for (int n = 0; n < 2; ++n) _Pragma("unroll") for (int k = 0; k < 2; ++k) \
;         acc[ai][bj][m][n] = __builtin_amdgcn_mfma_f32_16x16x32_bf16(Bt[n][k], At[m][k], acc[ai][bj][m][n], 0, 0, 0); __builtin_amdgcn_s_setprio(0); } while (0)
; #define PG8_WAIT_V(n) asm volatile("s_waitcnt vmcnt(" #n ")" ::: "memory")
; #define PG8_WAIT_L(n) asm volatile("s_waitcnt lgkmcnt(" #n ")" ::: "memory")
; #define PG8_BAR __builtin_amdgcn_s_barrier()
; template <class Epi, class Sched, bool ALIGN_EPI = false, bool SP2 = false>
; __device__ __forceinline__ void gemm_phase(PG8_LAS unsigned char* lds, const Gemm g, const Sched& S, const Epi& E) {
;     ...
;         for (int t = 0; t < nt; t += 2) {
;             const bool last = (t == nt - 2);
;             const char* a1 = cA + (size_t)(t + 1) * kstepA;
;             const char* a2 = last ? nA : cA + (size_t)(t + 2) * kstepA; const char* b2 = last ? nB : cB + (size_t)(t + 2) * kstepB;
;             const char* a3 = a2 + kstepA; const char* b3 = b2 + kstepB;
;     ...
;             PG8_LDB(B0, 1, 0); PG8_LDB(B1, 1, 1); PG8_SCHED; PG8_LDA(At, 1, 0); PG8_STAGE(PG8_SA(0, 1), a2 + hstepA, voffA);
;             PG8_WAIT_V(8); PG8_WAIT_L(0); PG8_BAR; PG8_MMA(0, 0, At, B0); PG8_MMA(0, 1, At, B1); PG8_BAR; PG8_SCHED;
;             PG8_LDA(At, 1, 1); PG8_STAGE(PG8_SB(1, 0), b3, voffB); PG8_STAGE(PG8_SB(1, 1), b3 + hstepB, voffB); PG8_STAGE(PG8_SA(1, 0), a3, voffA);
;             PG8_WAIT_V(8); PG8_WAIT_L(0); PG8_BAR; PG8_MMA(1, 0, At, B0); PG8_MMA(1, 1, At, B1); PG8_BAR; PG8_SCHED;
	s_setprio 0
	s_add_i32 s58, 0, 0x18000
	s_add_i32 s59, 0, 0x1c000
	v_add_u32_e32 v152, s58, v183
	v_add_u32_e32 v168, s59, v183
	ds_read_b128 v[140:143], v152
	ds_read_b128 v[144:147], v152 offset:1024
	ds_read_b128 v[148:151], v152 offset:2048
	ds_read_b128 v[152:155], v152 offset:3072
	ds_read_b128 v[156:159], v168
	ds_read_b128 v[160:163], v168 offset:1024
	ds_read_b128 v[164:167], v168 offset:2048
	ds_read_b128 v[168:171], v168 offset:3072
	s_mov_b32 m0, s10
	s_nop 0
	global_load_lds_dwordx4 v128, s[40:41]
	s_mov_b32 m0, s12
	s_nop 0
	global_load_lds_dwordx4 v130, s[40:41]
	s_add_u32 s40, s40, 0x4000
	s_addc_u32 s41, s41, 0
	s_mov_b32 m0, s13
	ds_read_b128 v[172:175], v204 offset:32768
	ds_read_b128 v[176:179], v204 offset:33792
	ds_read_b128 v[206:209], v204 offset:34816
	ds_read_b128 v[210:213], v204 offset:35840
	ds_read_b128 v[214:217], v204 offset:36864
	ds_read_b128 v[218:221], v204 offset:37888
	ds_read_b128 v[222:225], v204 offset:38912
	ds_read_b128 v[226:229], v204 offset:39936
	global_load_lds_dwordx4 v128, s[40:41]
	s_mov_b32 m0, s14
	s_nop 0
	global_load_lds_dwordx4 v130, s[40:41]
	s_waitcnt vmcnt(8)
	s_waitcnt lgkmcnt(0)
	s_setprio 1
	s_barrier
	v_mfma_f32_16x16x32_bf16 v[124:127], v[140:143], v[172:175], v[124:127]
	v_mfma_f32_16x16x32_bf16 v[120:123], v[148:151], v[172:175], v[120:123]
	v_mfma_f32_16x16x32_bf16 v[108:111], v[140:143], v[206:209], v[108:111]
	v_mfma_f32_16x16x32_bf16 v[104:107], v[148:151], v[206:209], v[104:107]
	v_mfma_f32_16x16x32_bf16 v[92:95], v[140:143], v[214:217], v[92:95]
	v_mfma_f32_16x16x32_bf16 v[88:91], v[148:151], v[214:217], v[88:91]
	v_mfma_f32_16x16x32_bf16 v[76:79], v[140:143], v[222:225], v[76:79]
	v_mfma_f32_16x16x32_bf16 v[72:75], v[148:151], v[222:225], v[72:75]
	v_mfma_f32_16x16x32_bf16 v[124:127], v[144:147], v[176:179], v[124:127]
	v_mfma_f32_16x16x32_bf16 v[120:123], v[152:155], v[176:179], v[120:123]
	v_mfma_f32_16x16x32_bf16 v[108:111], v[144:147], v[210:213], v[108:111]
	v_mfma_f32_16x16x32_bf16 v[104:107], v[152:155], v[210:213], v[104:107]
	v_mfma_f32_16x16x32_bf16 v[92:95], v[144:147], v[218:221], v[92:95]
	v_mfma_f32_16x16x32_bf16 v[88:91], v[152:155], v[218:221], v[88:91]
	v_mfma_f32_16x16x32_bf16 v[76:79], v[144:147], v[226:229], v[76:79]
	v_mfma_f32_16x16x32_bf16 v[72:75], v[152:155], v[226:229], v[72:75]
	v_mfma_f32_16x16x32_bf16 v[116:119], v[156:159], v[172:175], v[116:119]
	v_mfma_f32_16x16x32_bf16 v[112:115], v[164:167], v[172:175], v[112:115]
	v_mfma_f32_16x16x32_bf16 v[100:103], v[156:159], v[206:209], v[100:103]
	v_mfma_f32_16x16x32_bf16 v[96:99], v[164:167], v[206:209], v[96:99]
	v_mfma_f32_16x16x32_bf16 v[84:87], v[156:159], v[214:217], v[84:87]
	v_mfma_f32_16x16x32_bf16 v[80:83], v[164:167], v[214:217], v[80:83]
	v_mfma_f32_16x16x32_bf16 v[68:71], v[156:159], v[222:225], v[68:71]
	v_mfma_f32_16x16x32_bf16 v[64:67], v[164:167], v[222:225], v[64:67]
	v_mfma_f32_16x16x32_bf16 v[116:119], v[160:163], v[176:179], v[116:119]
	v_mfma_f32_16x16x32_bf16 v[112:115], v[168:171], v[176:179], v[112:115]
	v_mfma_f32_16x16x32_bf16 v[100:103], v[160:163], v[210:213], v[100:103]
	v_mfma_f32_16x16x32_bf16 v[96:99], v[168:171], v[210:213], v[96:99]
	v_mfma_f32_16x16x32_bf16 v[84:87], v[160:163], v[218:221], v[84:87]
	v_mfma_f32_16x16x32_bf16 v[80:83], v[168:171], v[218:221], v[80:83]
	v_mfma_f32_16x16x32_bf16 v[68:71], v[160:163], v[226:229], v[68:71]
	v_mfma_f32_16x16x32_bf16 v[64:67], v[168:171], v[226:229], v[64:67]
	s_barrier
	s_setprio 0
	s_add_u32 s40, s38, 0x8000
	s_addc_u32 s41, s39, 0
	s_add_i32 s58, s58, s2
	s_mov_b32 m0, s58
	ds_read_b128 v[172:175], v204 offset:49152
	ds_read_b128 v[176:179], v204 offset:50176
	ds_read_b128 v[206:209], v204 offset:51200
	ds_read_b128 v[210:213], v204 offset:52224
	ds_read_b128 v[214:217], v204 offset:53248
	ds_read_b128 v[218:221], v204 offset:54272
	ds_read_b128 v[222:225], v204 offset:55296
	ds_read_b128 v[226:229], v204 offset:56320
	global_load_lds_dwordx4 v128, s[40:41]
	s_add_i32 m0, s58, 0x2000
	s_add_u32 s38, s38, 0xc000
	s_addc_u32 s39, s39, 0
	global_load_lds_dwordx4 v130, s[40:41]
	s_add_i32 s40, s59, s2
	s_mov_b32 m0, s40
	s_nop 0
	global_load_lds_dwordx4 v128, s[38:39]
	s_add_i32 m0, s40, 0x2000
	s_nop 0
	global_load_lds_dwordx4 v130, s[38:39]
	s_mov_b32 m0, s15
	s_nop 0
	global_load_lds_dwordx4 v128, s[36:37]
	s_mov_b32 m0, s42
	s_nop 0
	global_load_lds_dwordx4 v130, s[36:37]
	s_waitcnt vmcnt(8)
	s_waitcnt lgkmcnt(0)
	s_setprio 1
	s_barrier
	v_mfma_f32_16x16x32_bf16 v[60:63], v[140:143], v[172:175], v[60:63]
	v_mfma_f32_16x16x32_bf16 v[56:59], v[148:151], v[172:175], v[56:59]
	v_mfma_f32_16x16x32_bf16 v[44:47], v[140:143], v[206:209], v[44:47]
	v_mfma_f32_16x16x32_bf16 v[40:43], v[148:151], v[206:209], v[40:43]
	v_mfma_f32_16x16x32_bf16 v[28:31], v[140:143], v[214:217], v[28:31]
	v_mfma_f32_16x16x32_bf16 v[24:27], v[148:151], v[214:217], v[24:27]
	v_mfma_f32_16x16x32_bf16 v[12:15], v[140:143], v[222:225], v[12:15]
	v_mfma_f32_16x16x32_bf16 v[8:11], v[148:151], v[222:225], v[8:11]
	v_mfma_f32_16x16x32_bf16 v[60:63], v[144:147], v[176:179], v[60:63]
	v_mfma_f32_16x16x32_bf16 v[56:59], v[152:155], v[176:179], v[56:59]
	v_mfma_f32_16x16x32_bf16 v[44:47], v[144:147], v[210:213], v[44:47]
	v_mfma_f32_16x16x32_bf16 v[40:43], v[152:155], v[210:213], v[40:43]
	v_mfma_f32_16x16x32_bf16 v[28:31], v[144:147], v[218:221], v[28:31]
	v_mfma_f32_16x16x32_bf16 v[24:27], v[152:155], v[218:221], v[24:27]
	v_mfma_f32_16x16x32_bf16 v[12:15], v[144:147], v[226:229], v[12:15]
	v_mfma_f32_16x16x32_bf16 v[8:11], v[152:155], v[226:229], v[8:11]
	v_mfma_f32_16x16x32_bf16 v[52:55], v[156:159], v[172:175], v[52:55]
	v_mfma_f32_16x16x32_bf16 v[48:51], v[164:167], v[172:175], v[48:51]
	v_mfma_f32_16x16x32_bf16 v[36:39], v[156:159], v[206:209], v[36:39]
	v_mfma_f32_16x16x32_bf16 v[32:35], v[164:167], v[206:209], v[32:35]
	v_mfma_f32_16x16x32_bf16 v[20:23], v[156:159], v[214:217], v[20:23]
	v_mfma_f32_16x16x32_bf16 v[16:19], v[164:167], v[214:217], v[16:19]
	v_mfma_f32_16x16x32_bf16 v[4:7], v[156:159], v[222:225], v[4:7]
	v_mfma_f32_16x16x32_bf16 v[0:3], v[164:167], v[222:225], v[0:3]
	v_mfma_f32_16x16x32_bf16 v[52:55], v[160:163], v[176:179], v[52:55]
	v_mfma_f32_16x16x32_bf16 v[48:51], v[168:171], v[176:179], v[48:51]
	v_mfma_f32_16x16x32_bf16 v[36:39], v[160:163], v[210:213], v[36:39]
	v_mfma_f32_16x16x32_bf16 v[32:35], v[168:171], v[210:213], v[32:35]
	v_mfma_f32_16x16x32_bf16 v[20:23], v[160:163], v[218:221], v[20:23]
	v_mfma_f32_16x16x32_bf16 v[16:19], v[168:171], v[218:221], v[16:19]
	v_mfma_f32_16x16x32_bf16 v[4:7], v[160:163], v[226:229], v[4:7]
	v_mfma_f32_16x16x32_bf16 v[0:3], v[168:171], v[226:229], v[0:3]
	s_barrier
	s_setprio 0
	s_add_u32 s34, s34, 0x10000
	s_addc_u32 s35, s35, 0
	s_add_u32 s55, s55, 0x10000
	s_addc_u32 s56, s56, 0
	s_cmp_ge_i32 s57, s54
	s_mov_b32 s36, s57
	s_cbranch_scc0 .LBB0_360
	s_and_b64 vcc, exec, s[24:25]
	s_cbranch_vccnz .LBB0_365
	s_mov_b64 s[34:35], -1
	s_cmp_gt_i32 s20, -1
	v_lshl_or_b32 v140, s53, 8, v184
	s_cbranch_scc1 .LBB0_366

; #define PG8_STAGE(bufoff, gbase, voff) do { _Pragma("unroll") for (int _i = 0; _i < 2; ++_i) \
;         __builtin_amdgcn_global_load_lds((const unsigned*)((const char*)(gbase) + (voff)[_i]), (PG8_LAS unsigned*)(lds + (bufoff) + ldsw + _i * 8192), 16, 0, 0); } while (0)
; #define PG8_LDA(dst, b, h) do { _Pragma("unroll") for (int m = 0; m < 4; ++m) _Pragma("unroll") for (int k = 0; k < 2; ++k) dst[m][k] = *(const PG8_LAS bf16x8*)(lds + PG8_SA(b, h) + aoff + m * 2048 + k * 1024); } while (0)
; #define PG8_LDB(dst, b, h) do { _Pragma("unroll") for (int n = 0; n < 2; ++n) _Pragma("unroll") for (int k = 0; k < 2; ++k) dst[n][k] = *(const PG8_LAS bf16x8*)(lds + PG8_SB(b, h) + boff + n * 2048 + k * 1024); } while (0)
; #define PG8_MMA(ai, bj, At, Bt) do { __builtin_amdgcn_s_setprio(1); _Pragma("unroll") for (int m = 0; m < 4; ++m) _Pragma("unroll") for (int n = 0; n < 2; ++n) _Pragma("unroll") for (int k = 0; k < 2; ++k) \
;         acc[ai][bj][m][n] = __builtin_amdgcn_mfma_f32_16x16x32_bf16(Bt[n][k], At[m][k], acc[ai][bj][m][n], 0, 0, 0); __builtin_amdgcn_s_setprio(0); } while (0)
; #define PG8_WAIT_V(n) asm volatile("s_waitcnt vmcnt(" #n ")" ::: "memory")
; #define PG8_WAIT_L(n) asm volatile("s_waitcnt lgkmcnt(" #n ")" ::: "memory")
; #define PG8_BAR __builtin_amdgcn_s_barrier()
; #define PG8_SCHED __builtin_amdgcn_sched_barrier(0)
; template <class Epi, class Sched, bool ALIGN_EPI = false, bool SP2 = false>
; __device__ __forceinline__ void gemm_phase(PG8_LAS unsigned char* lds, const Gemm g, const Sched& S, const Epi& E) {
;     ...
;             PG8_LDB(B0, 0, 0); PG8_LDB(B1, 0, 1); PG8_SCHED; PG8_LDA(At, 0, 0); PG8_STAGE(PG8_SA(1, 1), a1 + hstepA, voffA);
;             PG8_WAIT_V(8); PG8_WAIT_L(0); PG8_BAR; PG8_MMA(0, 0, At, B0); PG8_MMA(0, 1, At, B1); PG8_BAR; PG8_SCHED;
;             PG8_LDA(At, 0, 1); PG8_STAGE(PG8_SB(0, 0), b2, voffB); PG8_STAGE(PG8_SB(0, 1), b2 + hstepB, voffB); PG8_STAGE(PG8_SA(0, 0), a2, voffA);
;             PG8_WAIT_V(8); PG8_WAIT_L(0); PG8_BAR; PG8_MMA(1, 0, At, B0); PG8_MMA(1, 1, At, B1); PG8_BAR; PG8_SCHED;
.LBB0_616:
	ds_read_b128 v[132:135], v147
	ds_read_b128 v[136:139], v147 offset:1024
	ds_read_b128 v[140:143], v147 offset:2048
	ds_read_b128 v[152:155], v147 offset:3072
	ds_read_b128 v[156:159], v148
	ds_read_b128 v[160:163], v148 offset:1024
	ds_read_b128 v[164:167], v148 offset:2048
	ds_read_b128 v[168:171], v148 offset:3072
	s_add_u32 s40, s38, 0xfff80080
	s_addc_u32 s41, s39, -1
	s_cmp_eq_u32 s55, 28
	s_cselect_b32 s43, s1, s41
	s_cselect_b32 s42, s27, s40
	s_cselect_b32 s41, s25, s54
	s_cselect_b32 s40, s37, s53
	s_add_i32 m0, s13, 0xc000
	ds_read_b128 v[172:175], v149
	ds_read_b128 v[176:179], v149 offset:1024
	ds_read_b128 v[180:183], v149 offset:2048
	ds_read_b128 v[204:207], v149 offset:3072
	ds_read_b128 v[208:211], v149 offset:4096
	ds_read_b128 v[212:215], v149 offset:5120
	ds_read_b128 v[216:219], v149 offset:6144
	ds_read_b128 v[220:223], v149 offset:7168
	global_load_lds_dwordx4 v128, s[38:39]
	s_add_i32 m0, s13, 0xe000
	s_nop 0
	global_load_lds_dwordx4 v130, s[38:39]
	s_waitcnt vmcnt(8)
	s_waitcnt lgkmcnt(0)
	s_setprio 1
	s_barrier
	v_mfma_f32_16x16x32_bf16 v[124:127], v[132:135], v[172:175], v[124:127]
	v_mfma_f32_16x16x32_bf16 v[120:123], v[140:143], v[172:175], v[120:123]
	v_mfma_f32_16x16x32_bf16 v[108:111], v[132:135], v[180:183], v[108:111]
	v_mfma_f32_16x16x32_bf16 v[104:107], v[140:143], v[180:183], v[104:107]
	v_mfma_f32_16x16x32_bf16 v[92:95], v[132:135], v[208:211], v[92:95]
	v_mfma_f32_16x16x32_bf16 v[88:91], v[140:143], v[208:211], v[88:91]
	v_mfma_f32_16x16x32_bf16 v[76:79], v[132:135], v[216:219], v[76:79]
	v_mfma_f32_16x16x32_bf16 v[72:75], v[140:143], v[216:219], v[72:75]
	v_mfma_f32_16x16x32_bf16 v[124:127], v[136:139], v[176:179], v[124:127]
	v_mfma_f32_16x16x32_bf16 v[120:123], v[152:155], v[176:179], v[120:123]
	v_mfma_f32_16x16x32_bf16 v[108:111], v[136:139], v[204:207], v[108:111]
	v_mfma_f32_16x16x32_bf16 v[104:107], v[152:155], v[204:207], v[104:107]
	v_mfma_f32_16x16x32_bf16 v[92:95], v[136:139], v[212:215], v[92:95]
	v_mfma_f32_16x16x32_bf16 v[88:91], v[152:155], v[212:215], v[88:91]
	v_mfma_f32_16x16x32_bf16 v[76:79], v[136:139], v[220:223], v[76:79]
	v_mfma_f32_16x16x32_bf16 v[72:75], v[152:155], v[220:223], v[72:75]
	v_mfma_f32_16x16x32_bf16 v[116:119], v[156:159], v[172:175], v[116:119]
	v_mfma_f32_16x16x32_bf16 v[112:115], v[164:167], v[172:175], v[112:115]
	v_mfma_f32_16x16x32_bf16 v[100:103], v[156:159], v[180:183], v[100:103]
	v_mfma_f32_16x16x32_bf16 v[96:99], v[164:167], v[180:183], v[96:99]
	v_mfma_f32_16x16x32_bf16 v[84:87], v[156:159], v[208:211], v[84:87]
	v_mfma_f32_16x16x32_bf16 v[80:83], v[164:167], v[208:211], v[80:83]
	v_mfma_f32_16x16x32_bf16 v[68:71], v[156:159], v[216:219], v[68:71]
	v_mfma_f32_16x16x32_bf16 v[64:67], v[164:167], v[216:219], v[64:67]
	v_mfma_f32_16x16x32_bf16 v[116:119], v[160:163], v[176:179], v[116:119]
	v_mfma_f32_16x16x32_bf16 v[112:115], v[168:171], v[176:179], v[112:115]
	v_mfma_f32_16x16x32_bf16 v[100:103], v[160:163], v[204:207], v[100:103]
	v_mfma_f32_16x16x32_bf16 v[96:99], v[168:171], v[204:207], v[96:99]
	v_mfma_f32_16x16x32_bf16 v[84:87], v[160:163], v[212:215], v[84:87]
	v_mfma_f32_16x16x32_bf16 v[80:83], v[168:171], v[212:215], v[80:83]
	v_mfma_f32_16x16x32_bf16 v[68:71], v[160:163], v[220:223], v[68:71]
	v_mfma_f32_16x16x32_bf16 v[64:67], v[168:171], v[220:223], v[64:67]
	s_barrier
	s_add_u32 s98, s42, s20
	s_addc_u32 s99, s43, s21
	s_setprio 0
	s_add_i32 s56, s50, s2
	s_mov_b32 m0, s56
	ds_read_b128 v[172:175], v149 offset:16384
	ds_read_b128 v[176:179], v149 offset:17408
	ds_read_b128 v[180:183], v149 offset:18432
	ds_read_b128 v[204:207], v149 offset:19456
	ds_read_b128 v[208:211], v149 offset:20480
	ds_read_b128 v[212:215], v149 offset:21504
	ds_read_b128 v[216:219], v149 offset:22528
	ds_read_b128 v[220:223], v149 offset:23552
	global_load_lds_dwordx4 v194, s[40:41]
	s_add_i32 m0, s56, 0x2000
	s_add_u32 s56, s40, 0x4000
	s_addc_u32 s57, s41, 0
	s_add_i32 s58, s51, s2
	global_load_lds_dwordx4 v198, s[40:41]
	s_mov_b32 m0, s58
	s_nop 0
	global_load_lds_dwordx4 v194, s[56:57]
	s_add_i32 m0, s58, 0x2000
	s_nop 0
	global_load_lds_dwordx4 v198, s[56:57]
	s_waitcnt vmcnt(6)
	s_waitcnt lgkmcnt(0)
	s_setprio 1
	s_barrier
	v_mfma_f32_16x16x32_bf16 v[60:63], v[132:135], v[172:175], v[60:63]
	v_mfma_f32_16x16x32_bf16 v[56:59], v[140:143], v[172:175], v[56:59]
	v_mfma_f32_16x16x32_bf16 v[44:47], v[132:135], v[180:183], v[44:47]
	v_mfma_f32_16x16x32_bf16 v[40:43], v[140:143], v[180:183], v[40:43]
	v_mfma_f32_16x16x32_bf16 v[28:31], v[132:135], v[208:211], v[28:31]
	v_mfma_f32_16x16x32_bf16 v[24:27], v[140:143], v[208:211], v[24:27]
	v_mfma_f32_16x16x32_bf16 v[12:15], v[132:135], v[216:219], v[12:15]
	v_mfma_f32_16x16x32_bf16 v[8:11], v[140:143], v[216:219], v[8:11]
	v_mfma_f32_16x16x32_bf16 v[60:63], v[136:139], v[176:179], v[60:63]
	v_mfma_f32_16x16x32_bf16 v[56:59], v[152:155], v[176:179], v[56:59]
	v_mfma_f32_16x16x32_bf16 v[44:47], v[136:139], v[204:207], v[44:47]
	v_mfma_f32_16x16x32_bf16 v[40:43], v[152:155], v[204:207], v[40:43]
	v_mfma_f32_16x16x32_bf16 v[28:31], v[136:139], v[212:215], v[28:31]
	v_mfma_f32_16x16x32_bf16 v[24:27], v[152:155], v[212:215], v[24:27]
	v_mfma_f32_16x16x32_bf16 v[12:15], v[136:139], v[220:223], v[12:15]
	v_mfma_f32_16x16x32_bf16 v[8:11], v[152:155], v[220:223], v[8:11]
	v_mfma_f32_16x16x32_bf16 v[52:55], v[156:159], v[172:175], v[52:55]
	v_mfma_f32_16x16x32_bf16 v[48:51], v[164:167], v[172:175], v[48:51]
	v_mfma_f32_16x16x32_bf16 v[36:39], v[156:159], v[180:183], v[36:39]
	v_mfma_f32_16x16x32_bf16 v[32:35], v[164:167], v[180:183], v[32:35]
	v_mfma_f32_16x16x32_bf16 v[20:23], v[156:159], v[208:211], v[20:23]
	v_mfma_f32_16x16x32_bf16 v[16:19], v[164:167], v[208:211], v[16:19]
	v_mfma_f32_16x16x32_bf16 v[4:7], v[156:159], v[216:219], v[4:7]
	v_mfma_f32_16x16x32_bf16 v[0:3], v[164:167], v[216:219], v[0:3]
	v_mfma_f32_16x16x32_bf16 v[52:55], v[160:163], v[176:179], v[52:55]
	v_mfma_f32_16x16x32_bf16 v[48:51], v[168:171], v[176:179], v[48:51]
	v_mfma_f32_16x16x32_bf16 v[36:39], v[160:163], v[204:207], v[36:39]
	v_mfma_f32_16x16x32_bf16 v[32:35], v[168:171], v[204:207], v[32:35]
	v_mfma_f32_16x16x32_bf16 v[20:23], v[160:163], v[212:215], v[20:23]
	v_mfma_f32_16x16x32_bf16 v[16:19], v[168:171], v[212:215], v[16:19]
	v_mfma_f32_16x16x32_bf16 v[4:7], v[160:163], v[220:223], v[4:7]
	v_mfma_f32_16x16x32_bf16 v[0:3], v[168:171], v[220:223], v[0:3]
	s_barrier
; #define PG8_STAGE(bufoff, gbase, voff) do { _Pragma("unroll") for (int _i = 0; _i < 2; ++_i) \
;         __builtin_amdgcn_global_load_lds((const unsigned*)((const char*)(gbase) + (voff)[_i]), (PG8_LAS unsigned*)(lds + (bufoff) + ldsw + _i * 8192), 16, 0, 0); } while (0)
; #define PG8_LDA(dst, b, h) do { _Pragma("unroll") for (int m = 0; m < 4; ++m) _Pragma("unroll") for (int k = 0; k < 2; ++k) dst[m][k] = *(const PG8_LAS bf16x8*)(lds + PG8_SA(b, h) + aoff + m * 2048 + k * 1024); } while (0)
; #define PG8_LDB(dst, b, h) do { _Pragma("unroll") for (int n = 0; n < 2; ++n) _Pragma("unroll") for (int k = 0; k < 2; ++k) dst[n][k] = *(const PG8_LAS bf16x8*)(lds + PG8_SB(b, h) + boff + n * 2048 + k * 1024); } while (0)
; #define PG8_MMA(ai, bj, At, Bt) do { __builtin_amdgcn_s_setprio(1); _Pragma("unroll") for (int m = 0; m < 4; ++m) _Pragma("unroll") for (int n = 0; n < 2; ++n) _Pragma("unroll") for (int k = 0; k < 2; ++k) \
;         acc[ai][bj][m][n] = __builtin_amdgcn_mfma_f32_16x16x32_bf16(Bt[n][k], At[m][k], acc[ai][bj][m][n], 0, 0, 0); __builtin_amdgcn_s_setprio(0); } while (0)
; #define PG8_WAIT_V(n) asm volatile("s_waitcnt vmcnt(" #n ")" ::: "memory")
; #define PG8_WAIT_L(n) asm volatile("s_waitcnt lgkmcnt(" #n ")" ::: "memory")
; #define PG8_BAR __builtin_amdgcn_s_barrier()
; template <class Epi, class Sched, bool ALIGN_EPI = false, bool SP2 = false>
; __device__ __forceinline__ void gemm_phase(PG8_LAS unsigned char* lds, const Gemm g, const Sched& S, const Epi& E) {
;     ...
;         for (int t = 0; t < nt; t += 2) {
;             const bool last = (t == nt - 2);
;             const char* a1 = cA + (size_t)(t + 1) * kstepA;
;             const char* a2 = last ? nA : cA + (size_t)(t + 2) * kstepA; const char* b2 = last ? nB : cB + (size_t)(t + 2) * kstepB;
;             const char* a3 = a2 + kstepA; const char* b3 = b2 + kstepB;
;     ...
;             PG8_LDB(B0, 1, 0); PG8_LDB(B1, 1, 1); PG8_SCHED; PG8_LDA(At, 1, 0); PG8_STAGE(PG8_SA(0, 1), a2 + hstepA, voffA);
;             PG8_WAIT_V(8); PG8_WAIT_L(0); PG8_BAR; PG8_MMA(0, 0, At, B0); PG8_MMA(0, 1, At, B1); PG8_BAR; PG8_SCHED;
;             PG8_LDA(At, 1, 1); PG8_STAGE(PG8_SB(1, 0), b3, voffB); PG8_STAGE(PG8_SB(1, 1), b3 + hstepB, voffB); PG8_STAGE(PG8_SA(1, 0), a3, voffA);
;             PG8_WAIT_V(8); PG8_WAIT_L(0); PG8_BAR; PG8_MMA(1, 0, At, B0); PG8_MMA(1, 1, At, B1); PG8_BAR; PG8_SCHED;
	s_setprio 0
	s_add_i32 s56, 0, 0x18000
	v_add_u32_e32 v151, s56, v145
	s_add_i32 s57, 0, 0x1c000
	ds_read_b128 v[132:135], v151
	ds_read_b128 v[136:139], v151 offset:1024
	ds_read_b128 v[140:143], v151 offset:2048
	ds_read_b128 v[152:155], v151 offset:3072
	v_add_u32_e32 v151, s57, v145
	ds_read_b128 v[156:159], v151
	ds_read_b128 v[160:163], v151 offset:1024
	ds_read_b128 v[164:167], v151 offset:2048
	ds_read_b128 v[168:171], v151 offset:3072
	s_mov_b32 m0, s13
	s_nop 0
	global_load_lds_dwordx4 v192, s[42:43]
	s_mov_b32 m0, s14
	s_nop 0
	global_load_lds_dwordx4 v196, s[42:43]
	s_add_u32 s42, s42, 0x80000
	s_addc_u32 s43, s43, 0
	s_mov_b32 m0, s15
	ds_read_b128 v[172:175], v149 offset:32768
	ds_read_b128 v[176:179], v149 offset:33792
	ds_read_b128 v[180:183], v149 offset:34816
	ds_read_b128 v[204:207], v149 offset:35840
	ds_read_b128 v[208:211], v149 offset:36864
	ds_read_b128 v[212:215], v149 offset:37888
	ds_read_b128 v[216:219], v149 offset:38912
	ds_read_b128 v[220:223], v149 offset:39936
	global_load_lds_dwordx4 v192, s[42:43]
	s_mov_b32 m0, s44
	s_nop 0
	global_load_lds_dwordx4 v196, s[42:43]
	s_waitcnt vmcnt(8)
	s_waitcnt lgkmcnt(0)
	s_setprio 1
	s_barrier
	v_mfma_f32_16x16x32_bf16 v[124:127], v[132:135], v[172:175], v[124:127]
	v_mfma_f32_16x16x32_bf16 v[120:123], v[140:143], v[172:175], v[120:123]
	v_mfma_f32_16x16x32_bf16 v[108:111], v[132:135], v[180:183], v[108:111]
	v_mfma_f32_16x16x32_bf16 v[104:107], v[140:143], v[180:183], v[104:107]
	v_mfma_f32_16x16x32_bf16 v[92:95], v[132:135], v[208:211], v[92:95]
	v_mfma_f32_16x16x32_bf16 v[88:91], v[140:143], v[208:211], v[88:91]
	v_mfma_f32_16x16x32_bf16 v[76:79], v[132:135], v[216:219], v[76:79]
	v_mfma_f32_16x16x32_bf16 v[72:75], v[140:143], v[216:219], v[72:75]
	v_mfma_f32_16x16x32_bf16 v[124:127], v[136:139], v[176:179], v[124:127]
	v_mfma_f32_16x16x32_bf16 v[120:123], v[152:155], v[176:179], v[120:123]
	v_mfma_f32_16x16x32_bf16 v[108:111], v[136:139], v[204:207], v[108:111]
	v_mfma_f32_16x16x32_bf16 v[104:107], v[152:155], v[204:207], v[104:107]
	v_mfma_f32_16x16x32_bf16 v[92:95], v[136:139], v[212:215], v[92:95]
	v_mfma_f32_16x16x32_bf16 v[88:91], v[152:155], v[212:215], v[88:91]
	v_mfma_f32_16x16x32_bf16 v[76:79], v[136:139], v[220:223], v[76:79]
	v_mfma_f32_16x16x32_bf16 v[72:75], v[152:155], v[220:223], v[72:75]
	v_mfma_f32_16x16x32_bf16 v[116:119], v[156:159], v[172:175], v[116:119]
	v_mfma_f32_16x16x32_bf16 v[112:115], v[164:167], v[172:175], v[112:115]
	v_mfma_f32_16x16x32_bf16 v[100:103], v[156:159], v[180:183], v[100:103]
	v_mfma_f32_16x16x32_bf16 v[96:99], v[164:167], v[180:183], v[96:99]
	v_mfma_f32_16x16x32_bf16 v[84:87], v[156:159], v[208:211], v[84:87]
	v_mfma_f32_16x16x32_bf16 v[80:83], v[164:167], v[208:211], v[80:83]
	v_mfma_f32_16x16x32_bf16 v[68:71], v[156:159], v[216:219], v[68:71]
	v_mfma_f32_16x16x32_bf16 v[64:67], v[164:167], v[216:219], v[64:67]
	v_mfma_f32_16x16x32_bf16 v[116:119], v[160:163], v[176:179], v[116:119]
	v_mfma_f32_16x16x32_bf16 v[112:115], v[168:171], v[176:179], v[112:115]
	v_mfma_f32_16x16x32_bf16 v[100:103], v[160:163], v[204:207], v[100:103]
	v_mfma_f32_16x16x32_bf16 v[96:99], v[168:171], v[204:207], v[96:99]
	v_mfma_f32_16x16x32_bf16 v[84:87], v[160:163], v[212:215], v[84:87]
	v_mfma_f32_16x16x32_bf16 v[80:83], v[168:171], v[212:215], v[80:83]
	v_mfma_f32_16x16x32_bf16 v[68:71], v[160:163], v[220:223], v[68:71]
	v_mfma_f32_16x16x32_bf16 v[64:67], v[168:171], v[220:223], v[64:67]
	s_barrier
	s_setprio 0
	s_add_u32 s42, s40, 0x8000
	s_addc_u32 s43, s41, 0
	s_add_i32 s56, s56, s2
	s_mov_b32 m0, s56
	ds_read_b128 v[172:175], v149 offset:49152
	ds_read_b128 v[176:179], v149 offset:50176
	ds_read_b128 v[180:183], v149 offset:51200
	ds_read_b128 v[204:207], v149 offset:52224
	ds_read_b128 v[208:211], v149 offset:53248
	ds_read_b128 v[212:215], v149 offset:54272
	ds_read_b128 v[216:219], v149 offset:55296
	ds_read_b128 v[220:223], v149 offset:56320
	global_load_lds_dwordx4 v194, s[42:43]
	s_add_i32 m0, s56, 0x2000
	s_add_u32 s40, s40, 0xc000
	s_addc_u32 s41, s41, 0
	global_load_lds_dwordx4 v198, s[42:43]
	s_add_i32 s42, s57, s2
	s_mov_b32 m0, s42
	s_nop 0
	global_load_lds_dwordx4 v194, s[40:41]
	s_add_i32 m0, s42, 0x2000
	s_nop 0
	global_load_lds_dwordx4 v198, s[40:41]
	s_mov_b32 m0, s48
	s_nop 0
	global_load_lds_dwordx4 v192, s[98:99]
	s_mov_b32 m0, s49
	s_nop 0
	global_load_lds_dwordx4 v196, s[98:99]
	s_waitcnt vmcnt(8)
	s_waitcnt lgkmcnt(0)
	s_setprio 1
	s_barrier
	v_mfma_f32_16x16x32_bf16 v[60:63], v[132:135], v[172:175], v[60:63]
	v_mfma_f32_16x16x32_bf16 v[56:59], v[140:143], v[172:175], v[56:59]
	v_mfma_f32_16x16x32_bf16 v[44:47], v[132:135], v[180:183], v[44:47]
	v_mfma_f32_16x16x32_bf16 v[40:43], v[140:143], v[180:183], v[40:43]
	v_mfma_f32_16x16x32_bf16 v[28:31], v[132:135], v[208:211], v[28:31]
	v_mfma_f32_16x16x32_bf16 v[24:27], v[140:143], v[208:211], v[24:27]
	v_mfma_f32_16x16x32_bf16 v[12:15], v[132:135], v[216:219], v[12:15]
	v_mfma_f32_16x16x32_bf16 v[8:11], v[140:143], v[216:219], v[8:11]
	v_mfma_f32_16x16x32_bf16 v[60:63], v[136:139], v[176:179], v[60:63]
	v_mfma_f32_16x16x32_bf16 v[56:59], v[152:155], v[176:179], v[56:59]
	v_mfma_f32_16x16x32_bf16 v[44:47], v[136:139], v[204:207], v[44:47]
	v_mfma_f32_16x16x32_bf16 v[40:43], v[152:155], v[204:207], v[40:43]
	v_mfma_f32_16x16x32_bf16 v[28:31], v[136:139], v[212:215], v[28:31]
	v_mfma_f32_16x16x32_bf16 v[24:27], v[152:155], v[212:215], v[24:27]
	v_mfma_f32_16x16x32_bf16 v[12:15], v[136:139], v[220:223], v[12:15]
	v_mfma_f32_16x16x32_bf16 v[8:11], v[152:155], v[220:223], v[8:11]
	v_mfma_f32_16x16x32_bf16 v[52:55], v[156:159], v[172:175], v[52:55]
	v_mfma_f32_16x16x32_bf16 v[48:51], v[164:167], v[172:175], v[48:51]
	v_mfma_f32_16x16x32_bf16 v[36:39], v[156:159], v[180:183], v[36:39]
	v_mfma_f32_16x16x32_bf16 v[32:35], v[164:167], v[180:183], v[32:35]
	v_mfma_f32_16x16x32_bf16 v[20:23], v[156:159], v[208:211], v[20:23]
	v_mfma_f32_16x16x32_bf16 v[16:19], v[164:167], v[208:211], v[16:19]
	v_mfma_f32_16x16x32_bf16 v[4:7], v[156:159], v[216:219], v[4:7]
	v_mfma_f32_16x16x32_bf16 v[0:3], v[164:167], v[216:219], v[0:3]
	v_mfma_f32_16x16x32_bf16 v[52:55], v[160:163], v[176:179], v[52:55]
	v_mfma_f32_16x16x32_bf16 v[48:51], v[168:171], v[176:179], v[48:51]
	v_mfma_f32_16x16x32_bf16 v[36:39], v[160:163], v[204:207], v[36:39]
	v_mfma_f32_16x16x32_bf16 v[32:35], v[168:171], v[204:207], v[32:35]
	v_mfma_f32_16x16x32_bf16 v[20:23], v[160:163], v[212:215], v[20:23]
	v_mfma_f32_16x16x32_bf16 v[16:19], v[168:171], v[212:215], v[16:19]
	v_mfma_f32_16x16x32_bf16 v[4:7], v[160:163], v[220:223], v[4:7]
	v_mfma_f32_16x16x32_bf16 v[0:3], v[168:171], v[220:223], v[0:3]
	s_barrier
	s_setprio 0
	s_add_i32 s55, s55, 2
	s_add_u32 s53, s53, 0x10000
	s_addc_u32 s54, s54, 0
	s_add_u32 s38, s38, 0x100
	s_addc_u32 s39, s39, 0
	s_cmp_gt_u32 s55, 29
	s_cbranch_scc0 .LBB0_616
	s_and_b64 vcc, exec, s[22:23]
	s_cbranch_vccz .LBB0_619
	s_barrier

; #define PG8_STAGE(bufoff, gbase, voff) do { _Pragma("unroll") for (int _i = 0; _i < 2; ++_i) \
;         __builtin_amdgcn_global_load_lds((const unsigned*)((const char*)(gbase) + (voff)[_i]), (PG8_LAS unsigned*)(lds + (bufoff) + ldsw + _i * 8192), 16, 0, 0); } while (0)
; #define PG8_LDA(dst, b, h) do { _Pragma("unroll") for (int m = 0; m < 4; ++m) _Pragma("unroll") for (int k = 0; k < 2; ++k) dst[m][k] = *(const PG8_LAS bf16x8*)(lds + PG8_SA(b, h) + aoff + m * 2048 + k * 1024); } while (0)
; #define PG8_LDB(dst, b, h) do { _Pragma("unroll") for (int n = 0; n < 2; ++n) _Pragma("unroll") for (int k = 0; k < 2; ++k) dst[n][k] = *(const PG8_LAS bf16x8*)(lds + PG8_SB(b, h) + boff + n * 2048 + k * 1024); } while (0)
; #define PG8_MMA(ai, bj, At, Bt) do { __builtin_amdgcn_s_setprio(1); _Pragma("unroll") for (int m = 0; m < 4; ++m) _Pragma("unroll") for (int n = 0; n < 2; ++n) _Pragma("unroll") for (int k = 0; k < 2; ++k) \
;         acc[ai][bj][m][n] = __builtin_amdgcn_mfma_f32_16x16x32_bf16(Bt[n][k], At[m][k], acc[ai][bj][m][n], 0, 0, 0); __builtin_amdgcn_s_setprio(0); } while (0)
; #define PG8_WAIT_V(n) asm volatile("s_waitcnt vmcnt(" #n ")" ::: "memory")
; #define PG8_WAIT_L(n) asm volatile("s_waitcnt lgkmcnt(" #n ")" ::: "memory")
; #define PG8_BAR __builtin_amdgcn_s_barrier()
; #define PG8_SCHED __builtin_amdgcn_sched_barrier(0)
; template <class Epi, class Sched, bool ALIGN_EPI = false, bool SP2 = false>
; __device__ __forceinline__ void gemm_phase(PG8_LAS unsigned char* lds, const Gemm g, const Sched& S, const Epi& E) {
;     ...
;             PG8_LDB(B0, 0, 0); PG8_LDB(B1, 0, 1); PG8_SCHED; PG8_LDA(At, 0, 0); PG8_STAGE(PG8_SA(1, 1), a1 + hstepA, voffA);
;             PG8_WAIT_V(8); PG8_WAIT_L(0); PG8_BAR; PG8_MMA(0, 0, At, B0); PG8_MMA(0, 1, At, B1); PG8_BAR; PG8_SCHED;
;             PG8_LDA(At, 0, 1); PG8_STAGE(PG8_SB(0, 0), b2, voffB); PG8_STAGE(PG8_SB(0, 1), b2 + hstepB, voffB); PG8_STAGE(PG8_SA(0, 0), a2, voffA);
;             PG8_WAIT_V(8); PG8_WAIT_L(0); PG8_BAR; PG8_MMA(1, 0, At, B0); PG8_MMA(1, 1, At, B1); PG8_BAR; PG8_SCHED;
.LBB0_938:
	s_add_i32 s71, s48, 2
	s_add_u32 s49, s46, 0xfffc0080
	s_addc_u32 s50, s47, -1
	s_add_i32 s72, 0, 0x10000
	s_cmp_eq_u32 s68, s48
	s_cselect_b32 s51, s1, s50
	s_cselect_b32 s50, s31, s49
	s_cselect_b32 s49, s35, s70
	s_cselect_b32 s48, s37, s69
	s_add_i32 s74, 0, 0x14000
	v_add_u32_e32 v140, s72, v247
	v_add_u32_e32 v156, s74, v247
	ds_read_b128 v[128:131], v140
	ds_read_b128 v[132:135], v140 offset:1024
	ds_read_b128 v[136:139], v140 offset:2048
	ds_read_b128 v[140:143], v140 offset:3072
	ds_read_b128 v[144:147], v156
	ds_read_b128 v[148:151], v156 offset:1024
	ds_read_b128 v[152:155], v156 offset:2048
	ds_read_b128 v[156:159], v156 offset:3072
	s_add_i32 m0, s45, 0xc000
	ds_read_b128 v[160:163], v249
	ds_read_b128 v[164:167], v249 offset:1024
	ds_read_b128 v[168:171], v249 offset:2048
	ds_read_b128 v[172:175], v249 offset:3072
	ds_read_b128 v[176:179], v249 offset:4096
	ds_read_b128 v[180:183], v249 offset:5120
	ds_read_b128 v[184:187], v249 offset:6144
	ds_read_b128 v[188:191], v249 offset:7168
	global_load_lds_dwordx4 v212, s[46:47]
	s_add_i32 m0, s45, 0xe000
	s_nop 0
	global_load_lds_dwordx4 v214, s[46:47]
	s_waitcnt vmcnt(8)
	s_waitcnt lgkmcnt(0)
	s_setprio 1
	s_barrier
	v_mfma_f32_16x16x32_bf16 v[124:127], v[128:131], v[160:163], v[124:127]
	v_mfma_f32_16x16x32_bf16 v[120:123], v[136:139], v[160:163], v[120:123]
	v_mfma_f32_16x16x32_bf16 v[112:115], v[128:131], v[168:171], v[112:115]
	v_mfma_f32_16x16x32_bf16 v[104:107], v[136:139], v[168:171], v[104:107]
	v_mfma_f32_16x16x32_bf16 v[96:99], v[128:131], v[176:179], v[96:99]
	v_mfma_f32_16x16x32_bf16 v[88:91], v[136:139], v[176:179], v[88:91]
	v_mfma_f32_16x16x32_bf16 v[80:83], v[128:131], v[184:187], v[80:83]
	v_mfma_f32_16x16x32_bf16 v[72:75], v[136:139], v[184:187], v[72:75]
	v_mfma_f32_16x16x32_bf16 v[124:127], v[132:135], v[164:167], v[124:127]
	v_mfma_f32_16x16x32_bf16 v[120:123], v[140:143], v[164:167], v[120:123]
	v_mfma_f32_16x16x32_bf16 v[112:115], v[132:135], v[172:175], v[112:115]
	v_mfma_f32_16x16x32_bf16 v[104:107], v[140:143], v[172:175], v[104:107]
	v_mfma_f32_16x16x32_bf16 v[96:99], v[132:135], v[180:183], v[96:99]
	v_mfma_f32_16x16x32_bf16 v[88:91], v[140:143], v[180:183], v[88:91]
	v_mfma_f32_16x16x32_bf16 v[80:83], v[132:135], v[188:191], v[80:83]
	v_mfma_f32_16x16x32_bf16 v[72:75], v[140:143], v[188:191], v[72:75]
	v_mfma_f32_16x16x32_bf16 v[116:119], v[144:147], v[160:163], v[116:119]
	v_mfma_f32_16x16x32_bf16 v[108:111], v[152:155], v[160:163], v[108:111]
	v_mfma_f32_16x16x32_bf16 v[100:103], v[144:147], v[168:171], v[100:103]
	v_mfma_f32_16x16x32_bf16 v[92:95], v[152:155], v[168:171], v[92:95]
	v_mfma_f32_16x16x32_bf16 v[84:87], v[144:147], v[176:179], v[84:87]
	v_mfma_f32_16x16x32_bf16 v[76:79], v[152:155], v[176:179], v[76:79]
	v_mfma_f32_16x16x32_bf16 v[68:71], v[144:147], v[184:187], v[68:71]
	v_mfma_f32_16x16x32_bf16 v[64:67], v[152:155], v[184:187], v[64:67]
	v_mfma_f32_16x16x32_bf16 v[116:119], v[148:151], v[164:167], v[116:119]
	v_mfma_f32_16x16x32_bf16 v[108:111], v[156:159], v[164:167], v[108:111]
	v_mfma_f32_16x16x32_bf16 v[100:103], v[148:151], v[172:175], v[100:103]
	v_mfma_f32_16x16x32_bf16 v[92:95], v[156:159], v[172:175], v[92:95]
	v_mfma_f32_16x16x32_bf16 v[84:87], v[148:151], v[180:183], v[84:87]
	v_mfma_f32_16x16x32_bf16 v[76:79], v[156:159], v[180:183], v[76:79]
	v_mfma_f32_16x16x32_bf16 v[68:71], v[148:151], v[188:191], v[68:71]
	v_mfma_f32_16x16x32_bf16 v[64:67], v[156:159], v[188:191], v[64:67]
	s_barrier
	s_add_u32 s98, s48, s20
	s_addc_u32 s99, s49, s21
	s_add_u32 s100, s50, s20
	s_addc_u32 s101, s51, s21
	s_setprio 0
	s_add_i32 s72, s72, s56
	s_mov_b32 m0, s72
	ds_read_b128 v[160:163], v249 offset:16384
	ds_read_b128 v[164:167], v249 offset:17408
	ds_read_b128 v[168:171], v249 offset:18432
	ds_read_b128 v[172:175], v249 offset:19456
	ds_read_b128 v[176:179], v249 offset:20480
	ds_read_b128 v[180:183], v249 offset:21504
	ds_read_b128 v[184:187], v249 offset:22528
	ds_read_b128 v[188:191], v249 offset:23552
	global_load_lds_dwordx4 v206, s[48:49]
	s_add_i32 m0, s72, 0x2000
	s_add_u32 s72, s48, 0x40000
	s_addc_u32 s73, s49, 0
	s_add_i32 s74, s74, s56
	global_load_lds_dwordx4 v210, s[48:49]
	s_mov_b32 m0, s74
	s_nop 0
	global_load_lds_dwordx4 v206, s[72:73]
	s_add_i32 m0, s74, 0x2000
	s_nop 0
	global_load_lds_dwordx4 v210, s[72:73]
	s_waitcnt vmcnt(6)
	s_waitcnt lgkmcnt(0)
	s_setprio 1
	s_barrier
	v_mfma_f32_16x16x32_bf16 v[60:63], v[128:131], v[160:163], v[60:63]
	v_mfma_f32_16x16x32_bf16 v[56:59], v[136:139], v[160:163], v[56:59]
	v_mfma_f32_16x16x32_bf16 v[48:51], v[128:131], v[168:171], v[48:51]
	v_mfma_f32_16x16x32_bf16 v[40:43], v[136:139], v[168:171], v[40:43]
	v_mfma_f32_16x16x32_bf16 v[32:35], v[128:131], v[176:179], v[32:35]
	v_mfma_f32_16x16x32_bf16 v[24:27], v[136:139], v[176:179], v[24:27]
	v_mfma_f32_16x16x32_bf16 v[16:19], v[128:131], v[184:187], v[16:19]
	v_mfma_f32_16x16x32_bf16 v[8:11], v[136:139], v[184:187], v[8:11]
	v_mfma_f32_16x16x32_bf16 v[60:63], v[132:135], v[164:167], v[60:63]
	v_mfma_f32_16x16x32_bf16 v[56:59], v[140:143], v[164:167], v[56:59]
	v_mfma_f32_16x16x32_bf16 v[48:51], v[132:135], v[172:175], v[48:51]
	v_mfma_f32_16x16x32_bf16 v[40:43], v[140:143], v[172:175], v[40:43]
	v_mfma_f32_16x16x32_bf16 v[32:35], v[132:135], v[180:183], v[32:35]
	v_mfma_f32_16x16x32_bf16 v[24:27], v[140:143], v[180:183], v[24:27]
	v_mfma_f32_16x16x32_bf16 v[16:19], v[132:135], v[188:191], v[16:19]
	v_mfma_f32_16x16x32_bf16 v[8:11], v[140:143], v[188:191], v[8:11]
	v_mfma_f32_16x16x32_bf16 v[52:55], v[144:147], v[160:163], v[52:55]
	v_mfma_f32_16x16x32_bf16 v[44:47], v[152:155], v[160:163], v[44:47]
	v_mfma_f32_16x16x32_bf16 v[36:39], v[144:147], v[168:171], v[36:39]
	v_mfma_f32_16x16x32_bf16 v[28:31], v[152:155], v[168:171], v[28:31]
	v_mfma_f32_16x16x32_bf16 v[20:23], v[144:147], v[176:179], v[20:23]
	v_mfma_f32_16x16x32_bf16 v[12:15], v[152:155], v[176:179], v[12:15]
	v_mfma_f32_16x16x32_bf16 v[4:7], v[144:147], v[184:187], v[4:7]
	v_mfma_f32_16x16x32_bf16 v[0:3], v[152:155], v[184:187], v[0:3]
	v_mfma_f32_16x16x32_bf16 v[52:55], v[148:151], v[164:167], v[52:55]
	v_mfma_f32_16x16x32_bf16 v[44:47], v[156:159], v[164:167], v[44:47]
	v_mfma_f32_16x16x32_bf16 v[36:39], v[148:151], v[172:175], v[36:39]
	v_mfma_f32_16x16x32_bf16 v[28:31], v[156:159], v[172:175], v[28:31]
	v_mfma_f32_16x16x32_bf16 v[20:23], v[148:151], v[180:183], v[20:23]
	v_mfma_f32_16x16x32_bf16 v[12:15], v[156:159], v[180:183], v[12:15]
	v_mfma_f32_16x16x32_bf16 v[4:7], v[148:151], v[188:191], v[4:7]
	v_mfma_f32_16x16x32_bf16 v[0:3], v[156:159], v[188:191], v[0:3]
	s_barrier
; #define PG8_STAGE(bufoff, gbase, voff) do { _Pragma("unroll") for (int _i = 0; _i < 2; ++_i) \
;         __builtin_amdgcn_global_load_lds((const unsigned*)((const char*)(gbase) + (voff)[_i]), (PG8_LAS unsigned*)(lds + (bufoff) + ldsw + _i * 8192), 16, 0, 0); } while (0)
; #define PG8_LDA(dst, b, h) do { _Pragma("unroll") for (int m = 0; m < 4; ++m) _Pragma("unroll") for (int k = 0; k < 2; ++k) dst[m][k] = *(const PG8_LAS bf16x8*)(lds + PG8_SA(b, h) + aoff + m * 2048 + k * 1024); } while (0)
; #define PG8_LDB(dst, b, h) do { _Pragma("unroll") for (int n = 0; n < 2; ++n) _Pragma("unroll") for (int k = 0; k < 2; ++k) dst[n][k] = *(const PG8_LAS bf16x8*)(lds + PG8_SB(b, h) + boff + n * 2048 + k * 1024); } while (0)
; #define PG8_MMA(ai, bj, At, Bt) do { __builtin_amdgcn_s_setprio(1); _Pragma("unroll") for (int m = 0; m < 4; ++m) _Pragma("unroll") for (int n = 0; n < 2; ++n) _Pragma("unroll") for (int k = 0; k < 2; ++k) \
;         acc[ai][bj][m][n] = __builtin_amdgcn_mfma_f32_16x16x32_bf16(Bt[n][k], At[m][k], acc[ai][bj][m][n], 0, 0, 0); __builtin_amdgcn_s_setprio(0); } while (0)
; #define PG8_WAIT_V(n) asm volatile("s_waitcnt vmcnt(" #n ")" ::: "memory")
; #define PG8_WAIT_L(n) asm volatile("s_waitcnt lgkmcnt(" #n ")" ::: "memory")
; #define PG8_BAR __builtin_amdgcn_s_barrier()
; template <class Epi, class Sched, bool ALIGN_EPI = false, bool SP2 = false>
; __device__ __forceinline__ void gemm_phase(PG8_LAS unsigned char* lds, const Gemm g, const Sched& S, const Epi& E) {
;     ...
;         for (int t = 0; t < nt; t += 2) {
;             const bool last = (t == nt - 2);
;             const char* a1 = cA + (size_t)(t + 1) * kstepA;
;             const char* a2 = last ? nA : cA + (size_t)(t + 2) * kstepA; const char* b2 = last ? nB : cB + (size_t)(t + 2) * kstepB;
;             const char* a3 = a2 + kstepA; const char* b3 = b2 + kstepB;
;     ...
;             PG8_LDB(B0, 1, 0); PG8_LDB(B1, 1, 1); PG8_SCHED; PG8_LDA(At, 1, 0); PG8_STAGE(PG8_SA(0, 1), a2 + hstepA, voffA);
;             PG8_WAIT_V(8); PG8_WAIT_L(0); PG8_BAR; PG8_MMA(0, 0, At, B0); PG8_MMA(0, 1, At, B1); PG8_BAR; PG8_SCHED;
;             PG8_LDA(At, 1, 1); PG8_STAGE(PG8_SB(1, 0), b3, voffB); PG8_STAGE(PG8_SB(1, 1), b3 + hstepB, voffB); PG8_STAGE(PG8_SA(1, 0), a3, voffA);
;             PG8_WAIT_V(8); PG8_WAIT_L(0); PG8_BAR; PG8_MMA(1, 0, At, B0); PG8_MMA(1, 1, At, B1); PG8_BAR; PG8_SCHED;
	s_setprio 0
	s_add_i32 s72, 0, 0x18000
	s_add_i32 s73, 0, 0x1c000
	v_add_u32_e32 v140, s72, v247
	v_add_u32_e32 v156, s73, v247
	ds_read_b128 v[128:131], v140
	ds_read_b128 v[132:135], v140 offset:1024
	ds_read_b128 v[136:139], v140 offset:2048
	ds_read_b128 v[140:143], v140 offset:3072
	ds_read_b128 v[144:147], v156
	ds_read_b128 v[148:151], v156 offset:1024
	ds_read_b128 v[152:155], v156 offset:2048
	ds_read_b128 v[156:159], v156 offset:3072
	s_mov_b32 m0, s45
	s_nop 0
	global_load_lds_dwordx4 v204, s[50:51]
	s_mov_b32 m0, s57
	s_nop 0
	global_load_lds_dwordx4 v208, s[50:51]
	s_add_u32 s50, s50, 0x40000
	s_addc_u32 s51, s51, 0
	s_mov_b32 m0, s58
	ds_read_b128 v[160:163], v249 offset:32768
	ds_read_b128 v[164:167], v249 offset:33792
	ds_read_b128 v[168:171], v249 offset:34816
	ds_read_b128 v[172:175], v249 offset:35840
	ds_read_b128 v[176:179], v249 offset:36864
	ds_read_b128 v[180:183], v249 offset:37888
	ds_read_b128 v[184:187], v249 offset:38912
	ds_read_b128 v[188:191], v249 offset:39936
	global_load_lds_dwordx4 v204, s[50:51]
	s_mov_b32 m0, s59
	s_nop 0
	global_load_lds_dwordx4 v208, s[50:51]
	s_waitcnt vmcnt(8)
	s_waitcnt lgkmcnt(0)
	s_setprio 1
	s_barrier
	v_mfma_f32_16x16x32_bf16 v[124:127], v[128:131], v[160:163], v[124:127]
	v_mfma_f32_16x16x32_bf16 v[120:123], v[136:139], v[160:163], v[120:123]
	v_mfma_f32_16x16x32_bf16 v[112:115], v[128:131], v[168:171], v[112:115]
	v_mfma_f32_16x16x32_bf16 v[104:107], v[136:139], v[168:171], v[104:107]
	v_mfma_f32_16x16x32_bf16 v[96:99], v[128:131], v[176:179], v[96:99]
	v_mfma_f32_16x16x32_bf16 v[88:91], v[136:139], v[176:179], v[88:91]
	v_mfma_f32_16x16x32_bf16 v[80:83], v[128:131], v[184:187], v[80:83]
	v_mfma_f32_16x16x32_bf16 v[72:75], v[136:139], v[184:187], v[72:75]
	v_mfma_f32_16x16x32_bf16 v[124:127], v[132:135], v[164:167], v[124:127]
	v_mfma_f32_16x16x32_bf16 v[120:123], v[140:143], v[164:167], v[120:123]
	v_mfma_f32_16x16x32_bf16 v[112:115], v[132:135], v[172:175], v[112:115]
	v_mfma_f32_16x16x32_bf16 v[104:107], v[140:143], v[172:175], v[104:107]
	v_mfma_f32_16x16x32_bf16 v[96:99], v[132:135], v[180:183], v[96:99]
	v_mfma_f32_16x16x32_bf16 v[88:91], v[140:143], v[180:183], v[88:91]
	v_mfma_f32_16x16x32_bf16 v[80:83], v[132:135], v[188:191], v[80:83]
	v_mfma_f32_16x16x32_bf16 v[72:75], v[140:143], v[188:191], v[72:75]
	v_mfma_f32_16x16x32_bf16 v[116:119], v[144:147], v[160:163], v[116:119]
	v_mfma_f32_16x16x32_bf16 v[108:111], v[152:155], v[160:163], v[108:111]
	v_mfma_f32_16x16x32_bf16 v[100:103], v[144:147], v[168:171], v[100:103]
	v_mfma_f32_16x16x32_bf16 v[92:95], v[152:155], v[168:171], v[92:95]
	v_mfma_f32_16x16x32_bf16 v[84:87], v[144:147], v[176:179], v[84:87]
	v_mfma_f32_16x16x32_bf16 v[76:79], v[152:155], v[176:179], v[76:79]
	v_mfma_f32_16x16x32_bf16 v[68:71], v[144:147], v[184:187], v[68:71]
	v_mfma_f32_16x16x32_bf16 v[64:67], v[152:155], v[184:187], v[64:67]
	v_mfma_f32_16x16x32_bf16 v[116:119], v[148:151], v[164:167], v[116:119]
	v_mfma_f32_16x16x32_bf16 v[108:111], v[156:159], v[164:167], v[108:111]
	v_mfma_f32_16x16x32_bf16 v[100:103], v[148:151], v[172:175], v[100:103]
	v_mfma_f32_16x16x32_bf16 v[92:95], v[156:159], v[172:175], v[92:95]
	v_mfma_f32_16x16x32_bf16 v[84:87], v[148:151], v[180:183], v[84:87]
	v_mfma_f32_16x16x32_bf16 v[76:79], v[156:159], v[180:183], v[76:79]
	v_mfma_f32_16x16x32_bf16 v[68:71], v[148:151], v[188:191], v[68:71]
	v_mfma_f32_16x16x32_bf16 v[64:67], v[156:159], v[188:191], v[64:67]
	s_barrier
	s_setprio 0
	s_add_i32 s50, s72, s56
	s_mov_b32 m0, s50
	ds_read_b128 v[160:163], v249 offset:49152
	ds_read_b128 v[164:167], v249 offset:50176
	ds_read_b128 v[168:171], v249 offset:51200
	ds_read_b128 v[172:175], v249 offset:52224
	ds_read_b128 v[176:179], v249 offset:53248
	ds_read_b128 v[180:183], v249 offset:54272
	ds_read_b128 v[184:187], v249 offset:55296
	ds_read_b128 v[188:191], v249 offset:56320
	global_load_lds_dwordx4 v206, s[98:99]
	s_add_i32 m0, s50, 0x2000
	s_add_u32 s48, s48, 0x40080
	s_addc_u32 s49, s49, 0
	s_add_i32 s50, s73, s56
	global_load_lds_dwordx4 v210, s[98:99]
	s_mov_b32 m0, s50
	s_nop 0
	global_load_lds_dwordx4 v206, s[48:49]
	s_add_i32 m0, s50, 0x2000
	s_nop 0
	global_load_lds_dwordx4 v210, s[48:49]
	s_mov_b32 m0, s62
	s_nop 0
	global_load_lds_dwordx4 v204, s[100:101]
	s_mov_b32 m0, s63
	s_nop 0
	global_load_lds_dwordx4 v208, s[100:101]
	s_waitcnt vmcnt(8)
	s_waitcnt lgkmcnt(0)
	s_setprio 1
	s_barrier
	v_mfma_f32_16x16x32_bf16 v[60:63], v[128:131], v[160:163], v[60:63]
	v_mfma_f32_16x16x32_bf16 v[56:59], v[136:139], v[160:163], v[56:59]
	v_mfma_f32_16x16x32_bf16 v[48:51], v[128:131], v[168:171], v[48:51]
	v_mfma_f32_16x16x32_bf16 v[40:43], v[136:139], v[168:171], v[40:43]
	v_mfma_f32_16x16x32_bf16 v[32:35], v[128:131], v[176:179], v[32:35]
	v_mfma_f32_16x16x32_bf16 v[24:27], v[136:139], v[176:179], v[24:27]
	v_mfma_f32_16x16x32_bf16 v[16:19], v[128:131], v[184:187], v[16:19]
	v_mfma_f32_16x16x32_bf16 v[8:11], v[136:139], v[184:187], v[8:11]
	v_mfma_f32_16x16x32_bf16 v[60:63], v[132:135], v[164:167], v[60:63]
	v_mfma_f32_16x16x32_bf16 v[56:59], v[140:143], v[164:167], v[56:59]
	v_mfma_f32_16x16x32_bf16 v[48:51], v[132:135], v[172:175], v[48:51]
	v_mfma_f32_16x16x32_bf16 v[40:43], v[140:143], v[172:175], v[40:43]
	v_mfma_f32_16x16x32_bf16 v[32:35], v[132:135], v[180:183], v[32:35]
	v_mfma_f32_16x16x32_bf16 v[24:27], v[140:143], v[180:183], v[24:27]
	v_mfma_f32_16x16x32_bf16 v[16:19], v[132:135], v[188:191], v[16:19]
	v_mfma_f32_16x16x32_bf16 v[8:11], v[140:143], v[188:191], v[8:11]
	v_mfma_f32_16x16x32_bf16 v[52:55], v[144:147], v[160:163], v[52:55]
	v_mfma_f32_16x16x32_bf16 v[44:47], v[152:155], v[160:163], v[44:47]
	v_mfma_f32_16x16x32_bf16 v[36:39], v[144:147], v[168:171], v[36:39]
	v_mfma_f32_16x16x32_bf16 v[28:31], v[152:155], v[168:171], v[28:31]
	v_mfma_f32_16x16x32_bf16 v[20:23], v[144:147], v[176:179], v[20:23]
	v_mfma_f32_16x16x32_bf16 v[12:15], v[152:155], v[176:179], v[12:15]
	v_mfma_f32_16x16x32_bf16 v[4:7], v[144:147], v[184:187], v[4:7]
	v_mfma_f32_16x16x32_bf16 v[0:3], v[152:155], v[184:187], v[0:3]
	v_mfma_f32_16x16x32_bf16 v[52:55], v[148:151], v[164:167], v[52:55]
	v_mfma_f32_16x16x32_bf16 v[44:47], v[156:159], v[164:167], v[44:47]
	v_mfma_f32_16x16x32_bf16 v[36:39], v[148:151], v[172:175], v[36:39]
	v_mfma_f32_16x16x32_bf16 v[28:31], v[156:159], v[172:175], v[28:31]
	v_mfma_f32_16x16x32_bf16 v[20:23], v[148:151], v[180:183], v[20:23]
	v_mfma_f32_16x16x32_bf16 v[12:15], v[156:159], v[180:183], v[12:15]
	v_mfma_f32_16x16x32_bf16 v[4:7], v[148:151], v[188:191], v[4:7]
	v_mfma_f32_16x16x32_bf16 v[0:3], v[156:159], v[188:191], v[0:3]
	s_barrier
	s_setprio 0
	s_add_u32 s46, s46, 0x100
	s_addc_u32 s47, s47, 0
	s_add_u32 s69, s69, 0x100
	s_addc_u32 s70, s70, 0
	s_cmp_ge_i32 s71, s67
	s_mov_b32 s48, s71
	s_cbranch_scc0 .LBB0_938
	s_and_b64 vcc, exec, s[26:27]
	s_cbranch_vccnz .LBB0_943
	s_mov_b64 s[46:47], -1
	s_cmp_gt_i32 s18, -1
	v_lshl_or_b32 v218, s44, 8, v248
	s_cbranch_scc1 .LBB0_944

; #define PG8_STAGE(bufoff, gbase, voff) do { _Pragma("unroll") for (int _i = 0; _i < 2; ++_i) \
;         __builtin_amdgcn_global_load_lds((const unsigned*)((const char*)(gbase) + (voff)[_i]), (PG8_LAS unsigned*)(lds + (bufoff) + ldsw + _i * 8192), 16, 0, 0); } while (0)
; #define PG8_LDA(dst, b, h) do { _Pragma("unroll") for (int m = 0; m < 4; ++m) _Pragma("unroll") for (int k = 0; k < 2; ++k) dst[m][k] = *(const PG8_LAS bf16x8*)(lds + PG8_SA(b, h) + aoff + m * 2048 + k * 1024); } while (0)
; #define PG8_LDB(dst, b, h) do { _Pragma("unroll") for (int n = 0; n < 2; ++n) _Pragma("unroll") for (int k = 0; k < 2; ++k) dst[n][k] = *(const PG8_LAS bf16x8*)(lds + PG8_SB(b, h) + boff + n * 2048 + k * 1024); } while (0)
; #define PG8_MMA(ai, bj, At, Bt) do { __builtin_amdgcn_s_setprio(1); _Pragma("unroll") for (int m = 0; m < 4; ++m) _Pragma("unroll") for (int n = 0; n < 2; ++n) _Pragma("unroll") for (int k = 0; k < 2; ++k) \
;         acc[ai][bj][m][n] = __builtin_amdgcn_mfma_f32_16x16x32_bf16(Bt[n][k], At[m][k], acc[ai][bj][m][n], 0, 0, 0); __builtin_amdgcn_s_setprio(0); } while (0)
; #define PG8_WAIT_V(n) asm volatile("s_waitcnt vmcnt(" #n ")" ::: "memory")
; #define PG8_WAIT_L(n) asm volatile("s_waitcnt lgkmcnt(" #n ")" ::: "memory")
; #define PG8_BAR __builtin_amdgcn_s_barrier()
; #define PG8_SCHED __builtin_amdgcn_sched_barrier(0)
; template <class Epi, class Sched, bool ALIGN_EPI = false, bool SP2 = false>
; __device__ __forceinline__ void gemm_phase(PG8_LAS unsigned char* lds, const Gemm g, const Sched& S, const Epi& E) {
;     ...
;             PG8_LDB(B0, 0, 0); PG8_LDB(B1, 0, 1); PG8_SCHED; PG8_LDA(At, 0, 0); PG8_STAGE(PG8_SA(1, 1), a1 + hstepA, voffA);
;             PG8_WAIT_V(8); PG8_WAIT_L(0); PG8_BAR; PG8_MMA(0, 0, At, B0); PG8_MMA(0, 1, At, B1); PG8_BAR; PG8_SCHED;
;             PG8_LDA(At, 0, 1); PG8_STAGE(PG8_SB(0, 0), b2, voffB); PG8_STAGE(PG8_SB(0, 1), b2 + hstepB, voffB); PG8_STAGE(PG8_SA(0, 0), a2, voffA);
;             PG8_WAIT_V(8); PG8_WAIT_L(0); PG8_BAR; PG8_MMA(1, 0, At, B0); PG8_MMA(1, 1, At, B1); PG8_BAR; PG8_SCHED;
.LBB0_1113:
	ds_read_b128 v[136:139], v181
	ds_read_b128 v[140:143], v181 offset:1024
	ds_read_b128 v[144:147], v181 offset:2048
	ds_read_b128 v[148:151], v181 offset:3072
	ds_read_b128 v[152:155], v182
	ds_read_b128 v[156:159], v182 offset:1024
	ds_read_b128 v[160:163], v182 offset:2048
	ds_read_b128 v[164:167], v182 offset:3072
	s_add_i32 s60, s44, 2
	s_add_u32 s45, s42, 0xfff80080
	s_addc_u32 s46, s43, -1
	s_cmp_eq_u32 s57, s44
	s_cselect_b32 s44, s39, s58
	s_cselect_b32 s47, s25, s46
	s_cselect_b32 s46, s29, s45
	s_cselect_b32 s45, s27, s59
	s_add_i32 m0, s13, 0xc000
	ds_read_b128 v[168:171], v183
	ds_read_b128 v[172:175], v183 offset:1024
	ds_read_b128 v[186:189], v183 offset:2048
	ds_read_b128 v[204:207], v183 offset:3072
	ds_read_b128 v[208:211], v183 offset:4096
	ds_read_b128 v[212:215], v183 offset:5120
	ds_read_b128 v[216:219], v183 offset:6144
	ds_read_b128 v[220:223], v183 offset:7168
	global_load_lds_dwordx4 v128, s[42:43]
	s_add_i32 m0, s13, 0xe000
	s_nop 0
	global_load_lds_dwordx4 v130, s[42:43]
	s_waitcnt vmcnt(8)
	s_waitcnt lgkmcnt(0)
	s_setprio 1
	s_barrier
	v_mfma_f32_16x16x32_bf16 v[124:127], v[136:139], v[168:171], v[124:127]
	v_mfma_f32_16x16x32_bf16 v[120:123], v[144:147], v[168:171], v[120:123]
	v_mfma_f32_16x16x32_bf16 v[108:111], v[136:139], v[186:189], v[108:111]
	v_mfma_f32_16x16x32_bf16 v[104:107], v[144:147], v[186:189], v[104:107]
	v_mfma_f32_16x16x32_bf16 v[92:95], v[136:139], v[208:211], v[92:95]
	v_mfma_f32_16x16x32_bf16 v[88:91], v[144:147], v[208:211], v[88:91]
	v_mfma_f32_16x16x32_bf16 v[76:79], v[136:139], v[216:219], v[76:79]
	v_mfma_f32_16x16x32_bf16 v[72:75], v[144:147], v[216:219], v[72:75]
	v_mfma_f32_16x16x32_bf16 v[124:127], v[140:143], v[172:175], v[124:127]
	v_mfma_f32_16x16x32_bf16 v[120:123], v[148:151], v[172:175], v[120:123]
	v_mfma_f32_16x16x32_bf16 v[108:111], v[140:143], v[204:207], v[108:111]
	v_mfma_f32_16x16x32_bf16 v[104:107], v[148:151], v[204:207], v[104:107]
	v_mfma_f32_16x16x32_bf16 v[92:95], v[140:143], v[212:215], v[92:95]
	v_mfma_f32_16x16x32_bf16 v[88:91], v[148:151], v[212:215], v[88:91]
	v_mfma_f32_16x16x32_bf16 v[76:79], v[140:143], v[220:223], v[76:79]
	v_mfma_f32_16x16x32_bf16 v[72:75], v[148:151], v[220:223], v[72:75]
	v_mfma_f32_16x16x32_bf16 v[116:119], v[152:155], v[168:171], v[116:119]
	v_mfma_f32_16x16x32_bf16 v[112:115], v[160:163], v[168:171], v[112:115]
	v_mfma_f32_16x16x32_bf16 v[100:103], v[152:155], v[186:189], v[100:103]
	v_mfma_f32_16x16x32_bf16 v[96:99], v[160:163], v[186:189], v[96:99]
	v_mfma_f32_16x16x32_bf16 v[84:87], v[152:155], v[208:211], v[84:87]
	v_mfma_f32_16x16x32_bf16 v[80:83], v[160:163], v[208:211], v[80:83]
	v_mfma_f32_16x16x32_bf16 v[68:71], v[152:155], v[216:219], v[68:71]
	v_mfma_f32_16x16x32_bf16 v[64:67], v[160:163], v[216:219], v[64:67]
	v_mfma_f32_16x16x32_bf16 v[116:119], v[156:159], v[172:175], v[116:119]
	v_mfma_f32_16x16x32_bf16 v[112:115], v[164:167], v[172:175], v[112:115]
	v_mfma_f32_16x16x32_bf16 v[100:103], v[156:159], v[204:207], v[100:103]
	v_mfma_f32_16x16x32_bf16 v[96:99], v[164:167], v[204:207], v[96:99]
	v_mfma_f32_16x16x32_bf16 v[84:87], v[156:159], v[212:215], v[84:87]
	v_mfma_f32_16x16x32_bf16 v[80:83], v[164:167], v[212:215], v[80:83]
	v_mfma_f32_16x16x32_bf16 v[68:71], v[156:159], v[220:223], v[68:71]
	v_mfma_f32_16x16x32_bf16 v[64:67], v[164:167], v[220:223], v[64:67]
	s_barrier
	s_add_u32 s98, s44, s20
	s_addc_u32 s99, s45, s21
	s_add_u32 s100, s46, s20
	s_addc_u32 s101, s47, s21
	s_setprio 0
	s_add_i32 s61, s51, s2
	s_mov_b32 m0, s61
	ds_read_b128 v[168:171], v183 offset:16384
	ds_read_b128 v[172:175], v183 offset:17408
	ds_read_b128 v[186:189], v183 offset:18432
	ds_read_b128 v[204:207], v183 offset:19456
	ds_read_b128 v[208:211], v183 offset:20480
	ds_read_b128 v[212:215], v183 offset:21504
	ds_read_b128 v[216:219], v183 offset:22528
	ds_read_b128 v[220:223], v183 offset:23552
	global_load_lds_dwordx4 v192, s[44:45]
	s_add_i32 m0, s61, 0x2000
	s_add_u32 s62, s44, 0x80000
	s_addc_u32 s63, s45, 0
	s_add_i32 s61, s52, s2
	global_load_lds_dwordx4 v196, s[44:45]
	s_mov_b32 m0, s61
	s_nop 0
	global_load_lds_dwordx4 v192, s[62:63]
	s_add_i32 m0, s61, 0x2000
	s_nop 0
	global_load_lds_dwordx4 v196, s[62:63]
	s_waitcnt vmcnt(6)
	s_waitcnt lgkmcnt(0)
	s_setprio 1
	s_barrier
	v_mfma_f32_16x16x32_bf16 v[60:63], v[136:139], v[168:171], v[60:63]
	v_mfma_f32_16x16x32_bf16 v[56:59], v[144:147], v[168:171], v[56:59]
	v_mfma_f32_16x16x32_bf16 v[44:47], v[136:139], v[186:189], v[44:47]
	v_mfma_f32_16x16x32_bf16 v[40:43], v[144:147], v[186:189], v[40:43]
	v_mfma_f32_16x16x32_bf16 v[28:31], v[136:139], v[208:211], v[28:31]
	v_mfma_f32_16x16x32_bf16 v[24:27], v[144:147], v[208:211], v[24:27]
	v_mfma_f32_16x16x32_bf16 v[12:15], v[136:139], v[216:219], v[12:15]
	v_mfma_f32_16x16x32_bf16 v[8:11], v[144:147], v[216:219], v[8:11]
	v_mfma_f32_16x16x32_bf16 v[60:63], v[140:143], v[172:175], v[60:63]
	v_mfma_f32_16x16x32_bf16 v[56:59], v[148:151], v[172:175], v[56:59]
	v_mfma_f32_16x16x32_bf16 v[44:47], v[140:143], v[204:207], v[44:47]
	v_mfma_f32_16x16x32_bf16 v[40:43], v[148:151], v[204:207], v[40:43]
	v_mfma_f32_16x16x32_bf16 v[28:31], v[140:143], v[212:215], v[28:31]
	v_mfma_f32_16x16x32_bf16 v[24:27], v[148:151], v[212:215], v[24:27]
	v_mfma_f32_16x16x32_bf16 v[12:15], v[140:143], v[220:223], v[12:15]
	v_mfma_f32_16x16x32_bf16 v[8:11], v[148:151], v[220:223], v[8:11]
	v_mfma_f32_16x16x32_bf16 v[52:55], v[152:155], v[168:171], v[52:55]
	v_mfma_f32_16x16x32_bf16 v[48:51], v[160:163], v[168:171], v[48:51]
	v_mfma_f32_16x16x32_bf16 v[36:39], v[152:155], v[186:189], v[36:39]
	v_mfma_f32_16x16x32_bf16 v[32:35], v[160:163], v[186:189], v[32:35]
	v_mfma_f32_16x16x32_bf16 v[20:23], v[152:155], v[208:211], v[20:23]
	v_mfma_f32_16x16x32_bf16 v[16:19], v[160:163], v[208:211], v[16:19]
	v_mfma_f32_16x16x32_bf16 v[4:7], v[152:155], v[216:219], v[4:7]
	v_mfma_f32_16x16x32_bf16 v[0:3], v[160:163], v[216:219], v[0:3]
	v_mfma_f32_16x16x32_bf16 v[52:55], v[156:159], v[172:175], v[52:55]
	v_mfma_f32_16x16x32_bf16 v[48:51], v[164:167], v[172:175], v[48:51]
	v_mfma_f32_16x16x32_bf16 v[36:39], v[156:159], v[204:207], v[36:39]
	v_mfma_f32_16x16x32_bf16 v[32:35], v[164:167], v[204:207], v[32:35]
	v_mfma_f32_16x16x32_bf16 v[20:23], v[156:159], v[212:215], v[20:23]
	v_mfma_f32_16x16x32_bf16 v[16:19], v[164:167], v[212:215], v[16:19]
	v_mfma_f32_16x16x32_bf16 v[4:7], v[156:159], v[220:223], v[4:7]
	v_mfma_f32_16x16x32_bf16 v[0:3], v[164:167], v[220:223], v[0:3]
	s_barrier
; #define PG8_STAGE(bufoff, gbase, voff) do { _Pragma("unroll") for (int _i = 0; _i < 2; ++_i) \
;         __builtin_amdgcn_global_load_lds((const unsigned*)((const char*)(gbase) + (voff)[_i]), (PG8_LAS unsigned*)(lds + (bufoff) + ldsw + _i * 8192), 16, 0, 0); } while (0)
; #define PG8_LDA(dst, b, h) do { _Pragma("unroll") for (int m = 0; m < 4; ++m) _Pragma("unroll") for (int k = 0; k < 2; ++k) dst[m][k] = *(const PG8_LAS bf16x8*)(lds + PG8_SA(b, h) + aoff + m * 2048 + k * 1024); } while (0)
; #define PG8_LDB(dst, b, h) do { _Pragma("unroll") for (int n = 0; n < 2; ++n) _Pragma("unroll") for (int k = 0; k < 2; ++k) dst[n][k] = *(const PG8_LAS bf16x8*)(lds + PG8_SB(b, h) + boff + n * 2048 + k * 1024); } while (0)
; #define PG8_MMA(ai, bj, At, Bt) do { __builtin_amdgcn_s_setprio(1); _Pragma("unroll") for (int m = 0; m < 4; ++m) _Pragma("unroll") for (int n = 0; n < 2; ++n) _Pragma("unroll") for (int k = 0; k < 2; ++k) \
;         acc[ai][bj][m][n] = __builtin_amdgcn_mfma_f32_16x16x32_bf16(Bt[n][k], At[m][k], acc[ai][bj][m][n], 0, 0, 0); __builtin_amdgcn_s_setprio(0); } while (0)
; #define PG8_WAIT_V(n) asm volatile("s_waitcnt vmcnt(" #n ")" ::: "memory")
; #define PG8_WAIT_L(n) asm volatile("s_waitcnt lgkmcnt(" #n ")" ::: "memory")
; #define PG8_BAR __builtin_amdgcn_s_barrier()
; template <class Epi, class Sched, bool ALIGN_EPI = false, bool SP2 = false>
; __device__ __forceinline__ void gemm_phase(PG8_LAS unsigned char* lds, const Gemm g, const Sched& S, const Epi& E) {
;     ...
;         for (int t = 0; t < nt; t += 2) {
;             const bool last = (t == nt - 2);
;             const char* a1 = cA + (size_t)(t + 1) * kstepA;
;             const char* a2 = last ? nA : cA + (size_t)(t + 2) * kstepA; const char* b2 = last ? nB : cB + (size_t)(t + 2) * kstepB;
;             const char* a3 = a2 + kstepA; const char* b3 = b2 + kstepB;
;     ...
;             PG8_LDB(B0, 1, 0); PG8_LDB(B1, 1, 1); PG8_SCHED; PG8_LDA(At, 1, 0); PG8_STAGE(PG8_SA(0, 1), a2 + hstepA, voffA);
;             PG8_WAIT_V(8); PG8_WAIT_L(0); PG8_BAR; PG8_MMA(0, 0, At, B0); PG8_MMA(0, 1, At, B1); PG8_BAR; PG8_SCHED;
;             PG8_LDA(At, 1, 1); PG8_STAGE(PG8_SB(1, 0), b3, voffB); PG8_STAGE(PG8_SB(1, 1), b3 + hstepB, voffB); PG8_STAGE(PG8_SA(1, 0), a3, voffA);
;             PG8_WAIT_V(8); PG8_WAIT_L(0); PG8_BAR; PG8_MMA(1, 0, At, B0); PG8_MMA(1, 1, At, B1); PG8_BAR; PG8_SCHED;
	s_setprio 0
	s_add_i32 s61, 0, 0x18000
	s_add_i32 s62, 0, 0x1c000
	v_add_u32_e32 v148, s61, v179
	v_add_u32_e32 v164, s62, v179
	ds_read_b128 v[136:139], v148
	ds_read_b128 v[140:143], v148 offset:1024
	ds_read_b128 v[144:147], v148 offset:2048
	ds_read_b128 v[148:151], v148 offset:3072
	ds_read_b128 v[152:155], v164
	ds_read_b128 v[156:159], v164 offset:1024
	ds_read_b128 v[160:163], v164 offset:2048
	ds_read_b128 v[164:167], v164 offset:3072
	s_mov_b32 m0, s13
	s_nop 0
	global_load_lds_dwordx4 v192, s[46:47]
	s_mov_b32 m0, s14
	s_nop 0
	global_load_lds_dwordx4 v196, s[46:47]
	s_add_u32 s46, s46, 0x80000
	s_addc_u32 s47, s47, 0
	s_mov_b32 m0, s15
	ds_read_b128 v[168:171], v183 offset:32768
	ds_read_b128 v[172:175], v183 offset:33792
	ds_read_b128 v[186:189], v183 offset:34816
	ds_read_b128 v[204:207], v183 offset:35840
	ds_read_b128 v[208:211], v183 offset:36864
	ds_read_b128 v[212:215], v183 offset:37888
	ds_read_b128 v[216:219], v183 offset:38912
	ds_read_b128 v[220:223], v183 offset:39936
	global_load_lds_dwordx4 v192, s[46:47]
	s_mov_b32 m0, s41
	s_nop 0
	global_load_lds_dwordx4 v196, s[46:47]
	s_waitcnt vmcnt(8)
	s_waitcnt lgkmcnt(0)
	s_setprio 1
	s_barrier
	v_mfma_f32_16x16x32_bf16 v[124:127], v[136:139], v[168:171], v[124:127]
	v_mfma_f32_16x16x32_bf16 v[120:123], v[144:147], v[168:171], v[120:123]
	v_mfma_f32_16x16x32_bf16 v[108:111], v[136:139], v[186:189], v[108:111]
	v_mfma_f32_16x16x32_bf16 v[104:107], v[144:147], v[186:189], v[104:107]
	v_mfma_f32_16x16x32_bf16 v[92:95], v[136:139], v[208:211], v[92:95]
	v_mfma_f32_16x16x32_bf16 v[88:91], v[144:147], v[208:211], v[88:91]
	v_mfma_f32_16x16x32_bf16 v[76:79], v[136:139], v[216:219], v[76:79]
	v_mfma_f32_16x16x32_bf16 v[72:75], v[144:147], v[216:219], v[72:75]
	v_mfma_f32_16x16x32_bf16 v[124:127], v[140:143], v[172:175], v[124:127]
	v_mfma_f32_16x16x32_bf16 v[120:123], v[148:151], v[172:175], v[120:123]
	v_mfma_f32_16x16x32_bf16 v[108:111], v[140:143], v[204:207], v[108:111]
	v_mfma_f32_16x16x32_bf16 v[104:107], v[148:151], v[204:207], v[104:107]
	v_mfma_f32_16x16x32_bf16 v[92:95], v[140:143], v[212:215], v[92:95]
	v_mfma_f32_16x16x32_bf16 v[88:91], v[148:151], v[212:215], v[88:91]
	v_mfma_f32_16x16x32_bf16 v[76:79], v[140:143], v[220:223], v[76:79]
	v_mfma_f32_16x16x32_bf16 v[72:75], v[148:151], v[220:223], v[72:75]
	v_mfma_f32_16x16x32_bf16 v[116:119], v[152:155], v[168:171], v[116:119]
	v_mfma_f32_16x16x32_bf16 v[112:115], v[160:163], v[168:171], v[112:115]
	v_mfma_f32_16x16x32_bf16 v[100:103], v[152:155], v[186:189], v[100:103]
	v_mfma_f32_16x16x32_bf16 v[96:99], v[160:163], v[186:189], v[96:99]
	v_mfma_f32_16x16x32_bf16 v[84:87], v[152:155], v[208:211], v[84:87]
	v_mfma_f32_16x16x32_bf16 v[80:83], v[160:163], v[208:211], v[80:83]
	v_mfma_f32_16x16x32_bf16 v[68:71], v[152:155], v[216:219], v[68:71]
	v_mfma_f32_16x16x32_bf16 v[64:67], v[160:163], v[216:219], v[64:67]
	v_mfma_f32_16x16x32_bf16 v[116:119], v[156:159], v[172:175], v[116:119]
	v_mfma_f32_16x16x32_bf16 v[112:115], v[164:167], v[172:175], v[112:115]
	v_mfma_f32_16x16x32_bf16 v[100:103], v[156:159], v[204:207], v[100:103]
	v_mfma_f32_16x16x32_bf16 v[96:99], v[164:167], v[204:207], v[96:99]
	v_mfma_f32_16x16x32_bf16 v[84:87], v[156:159], v[212:215], v[84:87]
	v_mfma_f32_16x16x32_bf16 v[80:83], v[164:167], v[212:215], v[80:83]
	v_mfma_f32_16x16x32_bf16 v[68:71], v[156:159], v[220:223], v[68:71]
	v_mfma_f32_16x16x32_bf16 v[64:67], v[164:167], v[220:223], v[64:67]
	s_barrier
	s_setprio 0
	s_add_i32 s46, s61, s2
	s_mov_b32 m0, s46
	ds_read_b128 v[168:171], v183 offset:49152
	ds_read_b128 v[172:175], v183 offset:50176
	ds_read_b128 v[186:189], v183 offset:51200
	ds_read_b128 v[204:207], v183 offset:52224
	ds_read_b128 v[208:211], v183 offset:53248
	ds_read_b128 v[212:215], v183 offset:54272
	ds_read_b128 v[216:219], v183 offset:55296
	ds_read_b128 v[220:223], v183 offset:56320
	global_load_lds_dwordx4 v192, s[98:99]
	s_add_i32 m0, s46, 0x2000
	s_add_u32 s44, s44, 0x80080
	s_addc_u32 s45, s45, 0
	s_add_i32 s46, s62, s2
	global_load_lds_dwordx4 v196, s[98:99]
	s_mov_b32 m0, s46
	s_nop 0
	global_load_lds_dwordx4 v192, s[44:45]
	s_add_i32 m0, s46, 0x2000
	s_nop 0
	global_load_lds_dwordx4 v196, s[44:45]
	s_mov_b32 m0, s48
	s_nop 0
	global_load_lds_dwordx4 v192, s[100:101]
	s_mov_b32 m0, s49
	s_nop 0
	global_load_lds_dwordx4 v196, s[100:101]
	s_waitcnt vmcnt(8)
	s_waitcnt lgkmcnt(0)
	s_setprio 1
	s_barrier
	v_mfma_f32_16x16x32_bf16 v[60:63], v[136:139], v[168:171], v[60:63]
	v_mfma_f32_16x16x32_bf16 v[56:59], v[144:147], v[168:171], v[56:59]
	v_mfma_f32_16x16x32_bf16 v[44:47], v[136:139], v[186:189], v[44:47]
	v_mfma_f32_16x16x32_bf16 v[40:43], v[144:147], v[186:189], v[40:43]
	v_mfma_f32_16x16x32_bf16 v[28:31], v[136:139], v[208:211], v[28:31]
	v_mfma_f32_16x16x32_bf16 v[24:27], v[144:147], v[208:211], v[24:27]
	v_mfma_f32_16x16x32_bf16 v[12:15], v[136:139], v[216:219], v[12:15]
	v_mfma_f32_16x16x32_bf16 v[8:11], v[144:147], v[216:219], v[8:11]
	v_mfma_f32_16x16x32_bf16 v[60:63], v[140:143], v[172:175], v[60:63]
	v_mfma_f32_16x16x32_bf16 v[56:59], v[148:151], v[172:175], v[56:59]
	v_mfma_f32_16x16x32_bf16 v[44:47], v[140:143], v[204:207], v[44:47]
	v_mfma_f32_16x16x32_bf16 v[40:43], v[148:151], v[204:207], v[40:43]
	v_mfma_f32_16x16x32_bf16 v[28:31], v[140:143], v[212:215], v[28:31]
	v_mfma_f32_16x16x32_bf16 v[24:27], v[148:151], v[212:215], v[24:27]
	v_mfma_f32_16x16x32_bf16 v[12:15], v[140:143], v[220:223], v[12:15]
	v_mfma_f32_16x16x32_bf16 v[8:11], v[148:151], v[220:223], v[8:11]
	v_mfma_f32_16x16x32_bf16 v[52:55], v[152:155], v[168:171], v[52:55]
	v_mfma_f32_16x16x32_bf16 v[48:51], v[160:163], v[168:171], v[48:51]
	v_mfma_f32_16x16x32_bf16 v[36:39], v[152:155], v[186:189], v[36:39]
	v_mfma_f32_16x16x32_bf16 v[32:35], v[160:163], v[186:189], v[32:35]
	v_mfma_f32_16x16x32_bf16 v[20:23], v[152:155], v[208:211], v[20:23]
	v_mfma_f32_16x16x32_bf16 v[16:19], v[160:163], v[208:211], v[16:19]
	v_mfma_f32_16x16x32_bf16 v[4:7], v[152:155], v[216:219], v[4:7]
	v_mfma_f32_16x16x32_bf16 v[0:3], v[160:163], v[216:219], v[0:3]
	v_mfma_f32_16x16x32_bf16 v[52:55], v[156:159], v[172:175], v[52:55]
	v_mfma_f32_16x16x32_bf16 v[48:51], v[164:167], v[172:175], v[48:51]
	v_mfma_f32_16x16x32_bf16 v[36:39], v[156:159], v[204:207], v[36:39]
	v_mfma_f32_16x16x32_bf16 v[32:35], v[164:167], v[204:207], v[32:35]
	v_mfma_f32_16x16x32_bf16 v[20:23], v[156:159], v[212:215], v[20:23]
	v_mfma_f32_16x16x32_bf16 v[16:19], v[164:167], v[212:215], v[16:19]
	v_mfma_f32_16x16x32_bf16 v[4:7], v[156:159], v[220:223], v[4:7]
	v_mfma_f32_16x16x32_bf16 v[0:3], v[164:167], v[220:223], v[0:3]
	s_barrier
	s_setprio 0
	s_add_u32 s42, s42, 0x100
	s_addc_u32 s43, s43, 0
	s_add_u32 s58, s58, 0x100
	s_addc_u32 s59, s59, 0
	s_cmp_ge_i32 s60, s56
	s_mov_b32 s44, s60
	s_cbranch_scc0 .LBB0_1113
	s_and_b64 vcc, exec, s[22:23]
	s_cbranch_vccnz .LBB0_1118
	s_mov_b64 s[42:43], -1
	s_cmp_gt_i32 s16, -1
	v_lshl_or_b32 v136, s40, 8, v180
	s_cbranch_scc1 .LBB0_1119

; #define PG8_STAGE(bufoff, gbase, voff) do { _Pragma("unroll") for (int _i = 0; _i < 2; ++_i) \
;         __builtin_amdgcn_global_load_lds((const unsigned*)((const char*)(gbase) + (voff)[_i]), (PG8_LAS unsigned*)(lds + (bufoff) + ldsw + _i * 8192), 16, 0, 0); } while (0)
; #define PG8_LDA(dst, b, h) do { _Pragma("unroll") for (int m = 0; m < 4; ++m) _Pragma("unroll") for (int k = 0; k < 2; ++k) dst[m][k] = *(const PG8_LAS bf16x8*)(lds + PG8_SA(b, h) + aoff + m * 2048 + k * 1024); } while (0)
; #define PG8_LDB(dst, b, h) do { _Pragma("unroll") for (int n = 0; n < 2; ++n) _Pragma("unroll") for (int k = 0; k < 2; ++k) dst[n][k] = *(const PG8_LAS bf16x8*)(lds + PG8_SB(b, h) + boff + n * 2048 + k * 1024); } while (0)
; #define PG8_MMA(ai, bj, At, Bt) do { __builtin_amdgcn_s_setprio(1); _Pragma("unroll") for (int m = 0; m < 4; ++m) _Pragma("unroll") for (int n = 0; n < 2; ++n) _Pragma("unroll") for (int k = 0; k < 2; ++k) \
;         acc[ai][bj][m][n] = __builtin_amdgcn_mfma_f32_16x16x32_bf16(Bt[n][k], At[m][k], acc[ai][bj][m][n], 0, 0, 0); __builtin_amdgcn_s_setprio(0); } while (0)
; #define PG8_WAIT_V(n) asm volatile("s_waitcnt vmcnt(" #n ")" ::: "memory")
; #define PG8_WAIT_L(n) asm volatile("s_waitcnt lgkmcnt(" #n ")" ::: "memory")
; #define PG8_BAR __builtin_amdgcn_s_barrier()
; #define PG8_SCHED __builtin_amdgcn_sched_barrier(0)
; template <class Epi, class Sched, bool ALIGN_EPI = false, bool SP2 = false>
; __device__ __forceinline__ void gemm_phase(PG8_LAS unsigned char* lds, const Gemm g, const Sched& S, const Epi& E) {
;     ...
;             PG8_LDB(B0, 0, 0); PG8_LDB(B1, 0, 1); PG8_SCHED; PG8_LDA(At, 0, 0); PG8_STAGE(PG8_SA(1, 1), a1 + hstepA, voffA);
;             PG8_WAIT_V(8); PG8_WAIT_L(0); PG8_BAR; PG8_MMA(0, 0, At, B0); PG8_MMA(0, 1, At, B1); PG8_BAR; PG8_SCHED;
;             PG8_LDA(At, 0, 1); PG8_STAGE(PG8_SB(0, 0), b2, voffB); PG8_STAGE(PG8_SB(0, 1), b2 + hstepB, voffB); PG8_STAGE(PG8_SA(0, 0), a2, voffA);
;             PG8_WAIT_V(8); PG8_WAIT_L(0); PG8_BAR; PG8_MMA(1, 0, At, B0); PG8_MMA(1, 1, At, B1); PG8_BAR; PG8_SCHED;
.LBB0_1339:
	ds_read_b128 v[136:139], v129
	ds_read_b128 v[144:147], v129 offset:1024
	ds_read_b128 v[148:151], v129 offset:2048
	ds_read_b128 v[152:155], v129 offset:3072
	ds_read_b128 v[156:159], v141
	ds_read_b128 v[160:163], v141 offset:1024
	ds_read_b128 v[164:167], v141 offset:2048
	ds_read_b128 v[168:171], v141 offset:3072
	s_add_u32 s36, s34, 0xfff80080
	s_addc_u32 s37, s35, -1
	s_cmp_eq_u32 s53, 28
	s_cselect_b32 s39, s23, s37
	s_cselect_b32 s38, s49, s36
	s_cselect_b32 s37, s21, s52
	s_cselect_b32 s36, s50, s51
	s_add_i32 m0, s15, 0xc000
	ds_read_b128 v[172:175], v142
	ds_read_b128 v[176:179], v142 offset:1024
	ds_read_b128 v[180:183], v142 offset:2048
	ds_read_b128 v[184:187], v142 offset:3072
	ds_read_b128 v[188:191], v142 offset:4096
	ds_read_b128 v[204:207], v142 offset:5120
	ds_read_b128 v[208:211], v142 offset:6144
	ds_read_b128 v[212:215], v142 offset:7168
	global_load_lds_dwordx4 v132, s[34:35]
	s_add_i32 m0, s15, 0xe000
	s_nop 0
	global_load_lds_dwordx4 v134, s[34:35]
	s_waitcnt vmcnt(8)
	s_waitcnt lgkmcnt(0)
	s_setprio 1
	s_barrier
	v_mfma_f32_16x16x32_bf16 v[124:127], v[136:139], v[172:175], v[124:127]
	v_mfma_f32_16x16x32_bf16 v[120:123], v[148:151], v[172:175], v[120:123]
	v_mfma_f32_16x16x32_bf16 v[108:111], v[136:139], v[180:183], v[108:111]
	v_mfma_f32_16x16x32_bf16 v[104:107], v[148:151], v[180:183], v[104:107]
	v_mfma_f32_16x16x32_bf16 v[92:95], v[136:139], v[188:191], v[92:95]
	v_mfma_f32_16x16x32_bf16 v[88:91], v[148:151], v[188:191], v[88:91]
	v_mfma_f32_16x16x32_bf16 v[76:79], v[136:139], v[208:211], v[76:79]
	v_mfma_f32_16x16x32_bf16 v[72:75], v[148:151], v[208:211], v[72:75]
	v_mfma_f32_16x16x32_bf16 v[124:127], v[144:147], v[176:179], v[124:127]
	v_mfma_f32_16x16x32_bf16 v[120:123], v[152:155], v[176:179], v[120:123]
	v_mfma_f32_16x16x32_bf16 v[108:111], v[144:147], v[184:187], v[108:111]
	v_mfma_f32_16x16x32_bf16 v[104:107], v[152:155], v[184:187], v[104:107]
	v_mfma_f32_16x16x32_bf16 v[92:95], v[144:147], v[204:207], v[92:95]
	v_mfma_f32_16x16x32_bf16 v[88:91], v[152:155], v[204:207], v[88:91]
	v_mfma_f32_16x16x32_bf16 v[76:79], v[144:147], v[212:215], v[76:79]
	v_mfma_f32_16x16x32_bf16 v[72:75], v[152:155], v[212:215], v[72:75]
	v_mfma_f32_16x16x32_bf16 v[116:119], v[156:159], v[172:175], v[116:119]
	v_mfma_f32_16x16x32_bf16 v[112:115], v[164:167], v[172:175], v[112:115]
	v_mfma_f32_16x16x32_bf16 v[100:103], v[156:159], v[180:183], v[100:103]
	v_mfma_f32_16x16x32_bf16 v[96:99], v[164:167], v[180:183], v[96:99]
	v_mfma_f32_16x16x32_bf16 v[84:87], v[156:159], v[188:191], v[84:87]
	v_mfma_f32_16x16x32_bf16 v[80:83], v[164:167], v[188:191], v[80:83]
	v_mfma_f32_16x16x32_bf16 v[68:71], v[156:159], v[208:211], v[68:71]
	v_mfma_f32_16x16x32_bf16 v[64:67], v[164:167], v[208:211], v[64:67]
	v_mfma_f32_16x16x32_bf16 v[116:119], v[160:163], v[176:179], v[116:119]
	v_mfma_f32_16x16x32_bf16 v[112:115], v[168:171], v[176:179], v[112:115]
	v_mfma_f32_16x16x32_bf16 v[100:103], v[160:163], v[184:187], v[100:103]
	v_mfma_f32_16x16x32_bf16 v[96:99], v[168:171], v[184:187], v[96:99]
	v_mfma_f32_16x16x32_bf16 v[84:87], v[160:163], v[204:207], v[84:87]
	v_mfma_f32_16x16x32_bf16 v[80:83], v[168:171], v[204:207], v[80:83]
	v_mfma_f32_16x16x32_bf16 v[68:71], v[160:163], v[212:215], v[68:71]
	v_mfma_f32_16x16x32_bf16 v[64:67], v[168:171], v[212:215], v[64:67]
	s_barrier
	s_add_u32 s98, s38, s12
	s_addc_u32 s99, s39, s13
	s_setprio 0
	s_add_i32 s54, s46, s2
	s_mov_b32 m0, s54
	ds_read_b128 v[172:175], v142 offset:16384
	ds_read_b128 v[176:179], v142 offset:17408
	ds_read_b128 v[180:183], v142 offset:18432
	ds_read_b128 v[184:187], v142 offset:19456
	ds_read_b128 v[188:191], v142 offset:20480
	ds_read_b128 v[204:207], v142 offset:21504
	ds_read_b128 v[208:211], v142 offset:22528
	ds_read_b128 v[212:215], v142 offset:23552
	global_load_lds_dwordx4 v194, s[36:37]
	s_add_i32 m0, s54, 0x2000
	s_add_u32 s54, s36, 0x4000
	s_addc_u32 s55, s37, 0
	s_add_i32 s56, s47, s2
	global_load_lds_dwordx4 v198, s[36:37]
	s_mov_b32 m0, s56
	s_nop 0
	global_load_lds_dwordx4 v194, s[54:55]
	s_add_i32 m0, s56, 0x2000
	s_nop 0
	global_load_lds_dwordx4 v198, s[54:55]
	s_waitcnt vmcnt(6)
	s_waitcnt lgkmcnt(0)
	s_setprio 1
	s_barrier
	v_mfma_f32_16x16x32_bf16 v[60:63], v[136:139], v[172:175], v[60:63]
	v_mfma_f32_16x16x32_bf16 v[56:59], v[148:151], v[172:175], v[56:59]
	v_mfma_f32_16x16x32_bf16 v[44:47], v[136:139], v[180:183], v[44:47]
	v_mfma_f32_16x16x32_bf16 v[40:43], v[148:151], v[180:183], v[40:43]
	v_mfma_f32_16x16x32_bf16 v[28:31], v[136:139], v[188:191], v[28:31]
	v_mfma_f32_16x16x32_bf16 v[24:27], v[148:151], v[188:191], v[24:27]
	v_mfma_f32_16x16x32_bf16 v[12:15], v[136:139], v[208:211], v[12:15]
	v_mfma_f32_16x16x32_bf16 v[8:11], v[148:151], v[208:211], v[8:11]
	v_mfma_f32_16x16x32_bf16 v[60:63], v[144:147], v[176:179], v[60:63]
	v_mfma_f32_16x16x32_bf16 v[56:59], v[152:155], v[176:179], v[56:59]
	v_mfma_f32_16x16x32_bf16 v[44:47], v[144:147], v[184:187], v[44:47]
	v_mfma_f32_16x16x32_bf16 v[40:43], v[152:155], v[184:187], v[40:43]
	v_mfma_f32_16x16x32_bf16 v[28:31], v[144:147], v[204:207], v[28:31]
	v_mfma_f32_16x16x32_bf16 v[24:27], v[152:155], v[204:207], v[24:27]
	v_mfma_f32_16x16x32_bf16 v[12:15], v[144:147], v[212:215], v[12:15]
	v_mfma_f32_16x16x32_bf16 v[8:11], v[152:155], v[212:215], v[8:11]
	v_mfma_f32_16x16x32_bf16 v[52:55], v[156:159], v[172:175], v[52:55]
	v_mfma_f32_16x16x32_bf16 v[48:51], v[164:167], v[172:175], v[48:51]
	v_mfma_f32_16x16x32_bf16 v[36:39], v[156:159], v[180:183], v[36:39]
	v_mfma_f32_16x16x32_bf16 v[32:35], v[164:167], v[180:183], v[32:35]
	v_mfma_f32_16x16x32_bf16 v[20:23], v[156:159], v[188:191], v[20:23]
	v_mfma_f32_16x16x32_bf16 v[16:19], v[164:167], v[188:191], v[16:19]
	v_mfma_f32_16x16x32_bf16 v[4:7], v[156:159], v[208:211], v[4:7]
	v_mfma_f32_16x16x32_bf16 v[0:3], v[164:167], v[208:211], v[0:3]
	v_mfma_f32_16x16x32_bf16 v[52:55], v[160:163], v[176:179], v[52:55]
	v_mfma_f32_16x16x32_bf16 v[48:51], v[168:171], v[176:179], v[48:51]
	v_mfma_f32_16x16x32_bf16 v[36:39], v[160:163], v[184:187], v[36:39]
	v_mfma_f32_16x16x32_bf16 v[32:35], v[168:171], v[184:187], v[32:35]
	v_mfma_f32_16x16x32_bf16 v[20:23], v[160:163], v[204:207], v[20:23]
	v_mfma_f32_16x16x32_bf16 v[16:19], v[168:171], v[204:207], v[16:19]
	v_mfma_f32_16x16x32_bf16 v[4:7], v[160:163], v[212:215], v[4:7]
	v_mfma_f32_16x16x32_bf16 v[0:3], v[168:171], v[212:215], v[0:3]
	s_barrier
; #define PG8_STAGE(bufoff, gbase, voff) do { _Pragma("unroll") for (int _i = 0; _i < 2; ++_i) \
;         __builtin_amdgcn_global_load_lds((const unsigned*)((const char*)(gbase) + (voff)[_i]), (PG8_LAS unsigned*)(lds + (bufoff) + ldsw + _i * 8192), 16, 0, 0); } while (0)
; #define PG8_LDA(dst, b, h) do { _Pragma("unroll") for (int m = 0; m < 4; ++m) _Pragma("unroll") for (int k = 0; k < 2; ++k) dst[m][k] = *(const PG8_LAS bf16x8*)(lds + PG8_SA(b, h) + aoff + m * 2048 + k * 1024); } while (0)
; #define PG8_LDB(dst, b, h) do { _Pragma("unroll") for (int n = 0; n < 2; ++n) _Pragma("unroll") for (int k = 0; k < 2; ++k) dst[n][k] = *(const PG8_LAS bf16x8*)(lds + PG8_SB(b, h) + boff + n * 2048 + k * 1024); } while (0)
; #define PG8_MMA(ai, bj, At, Bt) do { __builtin_amdgcn_s_setprio(1); _Pragma("unroll") for (int m = 0; m < 4; ++m) _Pragma("unroll") for (int n = 0; n < 2; ++n) _Pragma("unroll") for (int k = 0; k < 2; ++k) \
;         acc[ai][bj][m][n] = __builtin_amdgcn_mfma_f32_16x16x32_bf16(Bt[n][k], At[m][k], acc[ai][bj][m][n], 0, 0, 0); __builtin_amdgcn_s_setprio(0); } while (0)
; #define PG8_WAIT_V(n) asm volatile("s_waitcnt vmcnt(" #n ")" ::: "memory")
; #define PG8_WAIT_L(n) asm volatile("s_waitcnt lgkmcnt(" #n ")" ::: "memory")
; #define PG8_BAR __builtin_amdgcn_s_barrier()
; template <class Epi, class Sched, bool ALIGN_EPI = false, bool SP2 = false>
; __device__ __forceinline__ void gemm_phase(PG8_LAS unsigned char* lds, const Gemm g, const Sched& S, const Epi& E) {
;     ...
;         for (int t = 0; t < nt; t += 2) {
;             const bool last = (t == nt - 2);
;             const char* a1 = cA + (size_t)(t + 1) * kstepA;
;             const char* a2 = last ? nA : cA + (size_t)(t + 2) * kstepA; const char* b2 = last ? nB : cB + (size_t)(t + 2) * kstepB;
;             const char* a3 = a2 + kstepA; const char* b3 = b2 + kstepB;
;     ...
;             PG8_LDB(B0, 1, 0); PG8_LDB(B1, 1, 1); PG8_SCHED; PG8_LDA(At, 1, 0); PG8_STAGE(PG8_SA(0, 1), a2 + hstepA, voffA);
;             PG8_WAIT_V(8); PG8_WAIT_L(0); PG8_BAR; PG8_MMA(0, 0, At, B0); PG8_MMA(0, 1, At, B1); PG8_BAR; PG8_SCHED;
;             PG8_LDA(At, 1, 1); PG8_STAGE(PG8_SB(1, 0), b3, voffB); PG8_STAGE(PG8_SB(1, 1), b3 + hstepB, voffB); PG8_STAGE(PG8_SA(1, 0), a3, voffA);
;             PG8_WAIT_V(8); PG8_WAIT_L(0); PG8_BAR; PG8_MMA(1, 0, At, B0); PG8_MMA(1, 1, At, B1); PG8_BAR; PG8_SCHED;
	s_setprio 0
	s_add_i32 s54, 0, 0x18000
	s_add_i32 s55, 0, 0x1c000
	v_add_u32_e32 v152, s54, v140
	v_add_u32_e32 v168, s55, v140
	ds_read_b128 v[136:139], v152
	ds_read_b128 v[144:147], v152 offset:1024
	ds_read_b128 v[148:151], v152 offset:2048
	ds_read_b128 v[152:155], v152 offset:3072
	ds_read_b128 v[156:159], v168
	ds_read_b128 v[160:163], v168 offset:1024
	ds_read_b128 v[164:167], v168 offset:2048
	ds_read_b128 v[168:171], v168 offset:3072
	s_mov_b32 m0, s15
	s_nop 0
	global_load_lds_dwordx4 v192, s[38:39]
	s_mov_b32 m0, s40
	s_nop 0
	global_load_lds_dwordx4 v196, s[38:39]
	s_add_u32 s38, s38, 0x80000
	s_addc_u32 s39, s39, 0
	s_mov_b32 m0, s41
	ds_read_b128 v[172:175], v142 offset:32768
	ds_read_b128 v[176:179], v142 offset:33792
	ds_read_b128 v[180:183], v142 offset:34816
	ds_read_b128 v[184:187], v142 offset:35840
	ds_read_b128 v[188:191], v142 offset:36864
	ds_read_b128 v[204:207], v142 offset:37888
	ds_read_b128 v[208:211], v142 offset:38912
	ds_read_b128 v[212:215], v142 offset:39936
	global_load_lds_dwordx4 v192, s[38:39]
	s_mov_b32 m0, s42
	s_nop 0
	global_load_lds_dwordx4 v196, s[38:39]
	s_waitcnt vmcnt(8)
	s_waitcnt lgkmcnt(0)
	s_setprio 1
	s_barrier
	v_mfma_f32_16x16x32_bf16 v[124:127], v[136:139], v[172:175], v[124:127]
	v_mfma_f32_16x16x32_bf16 v[120:123], v[148:151], v[172:175], v[120:123]
	v_mfma_f32_16x16x32_bf16 v[108:111], v[136:139], v[180:183], v[108:111]
	v_mfma_f32_16x16x32_bf16 v[104:107], v[148:151], v[180:183], v[104:107]
	v_mfma_f32_16x16x32_bf16 v[92:95], v[136:139], v[188:191], v[92:95]
	v_mfma_f32_16x16x32_bf16 v[88:91], v[148:151], v[188:191], v[88:91]
	v_mfma_f32_16x16x32_bf16 v[76:79], v[136:139], v[208:211], v[76:79]
	v_mfma_f32_16x16x32_bf16 v[72:75], v[148:151], v[208:211], v[72:75]
	v_mfma_f32_16x16x32_bf16 v[124:127], v[144:147], v[176:179], v[124:127]
	v_mfma_f32_16x16x32_bf16 v[120:123], v[152:155], v[176:179], v[120:123]
	v_mfma_f32_16x16x32_bf16 v[108:111], v[144:147], v[184:187], v[108:111]
	v_mfma_f32_16x16x32_bf16 v[104:107], v[152:155], v[184:187], v[104:107]
	v_mfma_f32_16x16x32_bf16 v[92:95], v[144:147], v[204:207], v[92:95]
	v_mfma_f32_16x16x32_bf16 v[88:91], v[152:155], v[204:207], v[88:91]
	v_mfma_f32_16x16x32_bf16 v[76:79], v[144:147], v[212:215], v[76:79]
	v_mfma_f32_16x16x32_bf16 v[72:75], v[152:155], v[212:215], v[72:75]
	v_mfma_f32_16x16x32_bf16 v[116:119], v[156:159], v[172:175], v[116:119]
	v_mfma_f32_16x16x32_bf16 v[112:115], v[164:167], v[172:175], v[112:115]
	v_mfma_f32_16x16x32_bf16 v[100:103], v[156:159], v[180:183], v[100:103]
	v_mfma_f32_16x16x32_bf16 v[96:99], v[164:167], v[180:183], v[96:99]
	v_mfma_f32_16x16x32_bf16 v[84:87], v[156:159], v[188:191], v[84:87]
	v_mfma_f32_16x16x32_bf16 v[80:83], v[164:167], v[188:191], v[80:83]
	v_mfma_f32_16x16x32_bf16 v[68:71], v[156:159], v[208:211], v[68:71]
	v_mfma_f32_16x16x32_bf16 v[64:67], v[164:167], v[208:211], v[64:67]
	v_mfma_f32_16x16x32_bf16 v[116:119], v[160:163], v[176:179], v[116:119]
	v_mfma_f32_16x16x32_bf16 v[112:115], v[168:171], v[176:179], v[112:115]
	v_mfma_f32_16x16x32_bf16 v[100:103], v[160:163], v[184:187], v[100:103]
	v_mfma_f32_16x16x32_bf16 v[96:99], v[168:171], v[184:187], v[96:99]
	v_mfma_f32_16x16x32_bf16 v[84:87], v[160:163], v[204:207], v[84:87]
	v_mfma_f32_16x16x32_bf16 v[80:83], v[168:171], v[204:207], v[80:83]
	v_mfma_f32_16x16x32_bf16 v[68:71], v[160:163], v[212:215], v[68:71]
	v_mfma_f32_16x16x32_bf16 v[64:67], v[168:171], v[212:215], v[64:67]
	s_barrier
	s_setprio 0
	s_add_u32 s38, s36, 0x8000
	s_addc_u32 s39, s37, 0
	s_add_i32 s54, s54, s2
	s_mov_b32 m0, s54
	ds_read_b128 v[172:175], v142 offset:49152
	ds_read_b128 v[176:179], v142 offset:50176
	ds_read_b128 v[180:183], v142 offset:51200
	ds_read_b128 v[184:187], v142 offset:52224
	ds_read_b128 v[188:191], v142 offset:53248
	ds_read_b128 v[204:207], v142 offset:54272
	ds_read_b128 v[208:211], v142 offset:55296
	ds_read_b128 v[212:215], v142 offset:56320
	global_load_lds_dwordx4 v194, s[38:39]
	s_add_i32 m0, s54, 0x2000
	s_add_u32 s36, s36, 0xc000
	s_addc_u32 s37, s37, 0
	global_load_lds_dwordx4 v198, s[38:39]
	s_add_i32 s38, s55, s2
	s_mov_b32 m0, s38
	s_nop 0
	global_load_lds_dwordx4 v194, s[36:37]
	s_add_i32 m0, s38, 0x2000
	s_nop 0
	global_load_lds_dwordx4 v198, s[36:37]
	s_mov_b32 m0, s43
	s_nop 0
	global_load_lds_dwordx4 v192, s[98:99]
	s_mov_b32 m0, s44
	s_nop 0
	global_load_lds_dwordx4 v196, s[98:99]
	s_waitcnt vmcnt(8)
	s_waitcnt lgkmcnt(0)
	s_setprio 1
	s_barrier
	v_mfma_f32_16x16x32_bf16 v[60:63], v[136:139], v[172:175], v[60:63]
	v_mfma_f32_16x16x32_bf16 v[56:59], v[148:151], v[172:175], v[56:59]
	v_mfma_f32_16x16x32_bf16 v[44:47], v[136:139], v[180:183], v[44:47]
	v_mfma_f32_16x16x32_bf16 v[40:43], v[148:151], v[180:183], v[40:43]
	v_mfma_f32_16x16x32_bf16 v[28:31], v[136:139], v[188:191], v[28:31]
	v_mfma_f32_16x16x32_bf16 v[24:27], v[148:151], v[188:191], v[24:27]
	v_mfma_f32_16x16x32_bf16 v[12:15], v[136:139], v[208:211], v[12:15]
	v_mfma_f32_16x16x32_bf16 v[8:11], v[148:151], v[208:211], v[8:11]
	v_mfma_f32_16x16x32_bf16 v[60:63], v[144:147], v[176:179], v[60:63]
	v_mfma_f32_16x16x32_bf16 v[56:59], v[152:155], v[176:179], v[56:59]
	v_mfma_f32_16x16x32_bf16 v[44:47], v[144:147], v[184:187], v[44:47]
	v_mfma_f32_16x16x32_bf16 v[40:43], v[152:155], v[184:187], v[40:43]
	v_mfma_f32_16x16x32_bf16 v[28:31], v[144:147], v[204:207], v[28:31]
	v_mfma_f32_16x16x32_bf16 v[24:27], v[152:155], v[204:207], v[24:27]
	v_mfma_f32_16x16x32_bf16 v[12:15], v[144:147], v[212:215], v[12:15]
	v_mfma_f32_16x16x32_bf16 v[8:11], v[152:155], v[212:215], v[8:11]
	v_mfma_f32_16x16x32_bf16 v[52:55], v[156:159], v[172:175], v[52:55]
	v_mfma_f32_16x16x32_bf16 v[48:51], v[164:167], v[172:175], v[48:51]
	v_mfma_f32_16x16x32_bf16 v[36:39], v[156:159], v[180:183], v[36:39]
	v_mfma_f32_16x16x32_bf16 v[32:35], v[164:167], v[180:183], v[32:35]
	v_mfma_f32_16x16x32_bf16 v[20:23], v[156:159], v[188:191], v[20:23]
	v_mfma_f32_16x16x32_bf16 v[16:19], v[164:167], v[188:191], v[16:19]
	v_mfma_f32_16x16x32_bf16 v[4:7], v[156:159], v[208:211], v[4:7]
	v_mfma_f32_16x16x32_bf16 v[0:3], v[164:167], v[208:211], v[0:3]
	v_mfma_f32_16x16x32_bf16 v[52:55], v[160:163], v[176:179], v[52:55]
	v_mfma_f32_16x16x32_bf16 v[48:51], v[168:171], v[176:179], v[48:51]
	v_mfma_f32_16x16x32_bf16 v[36:39], v[160:163], v[184:187], v[36:39]
	v_mfma_f32_16x16x32_bf16 v[32:35], v[168:171], v[184:187], v[32:35]
	v_mfma_f32_16x16x32_bf16 v[20:23], v[160:163], v[204:207], v[20:23]
	v_mfma_f32_16x16x32_bf16 v[16:19], v[168:171], v[204:207], v[16:19]
	v_mfma_f32_16x16x32_bf16 v[4:7], v[160:163], v[212:215], v[4:7]
	v_mfma_f32_16x16x32_bf16 v[0:3], v[168:171], v[212:215], v[0:3]
	s_barrier
	s_setprio 0
	s_add_i32 s53, s53, 2
	s_add_u32 s51, s51, 0x10000
	s_addc_u32 s52, s52, 0
	s_add_u32 s34, s34, 0x100
	s_addc_u32 s35, s35, 0
	s_cmp_gt_u32 s53, 29
	s_cbranch_scc0 .LBB0_1339
	s_and_b64 vcc, exec, s[18:19]
	s_cbranch_vccz .LBB0_1342
	s_barrier

; #define PG8_STAGE(bufoff, gbase, voff) do { _Pragma("unroll") for (int _i = 0; _i < 2; ++_i) \
;         __builtin_amdgcn_global_load_lds((const unsigned*)((const char*)(gbase) + (voff)[_i]), (PG8_LAS unsigned*)(lds + (bufoff) + ldsw + _i * 8192), 16, 0, 0); } while (0)
; #define PG8_LDA(dst, b, h) do { _Pragma("unroll") for (int m = 0; m < 4; ++m) _Pragma("unroll") for (int k = 0; k < 2; ++k) dst[m][k] = *(const PG8_LAS bf16x8*)(lds + PG8_SA(b, h) + aoff + m * 2048 + k * 1024); } while (0)
; #define PG8_LDB(dst, b, h) do { _Pragma("unroll") for (int n = 0; n < 2; ++n) _Pragma("unroll") for (int k = 0; k < 2; ++k) dst[n][k] = *(const PG8_LAS bf16x8*)(lds + PG8_SB(b, h) + boff + n * 2048 + k * 1024); } while (0)
; #define PG8_MMA(ai, bj, At, Bt) do { __builtin_amdgcn_s_setprio(1); _Pragma("unroll") for (int m = 0; m < 4; ++m) _Pragma("unroll") for (int n = 0; n < 2; ++n) _Pragma("unroll") for (int k = 0; k < 2; ++k) \
;         acc[ai][bj][m][n] = __builtin_amdgcn_mfma_f32_16x16x32_bf16(Bt[n][k], At[m][k], acc[ai][bj][m][n], 0, 0, 0); __builtin_amdgcn_s_setprio(0); } while (0)
; #define PG8_WAIT_V(n) asm volatile("s_waitcnt vmcnt(" #n ")" ::: "memory")
; #define PG8_WAIT_L(n) asm volatile("s_waitcnt lgkmcnt(" #n ")" ::: "memory")
; #define PG8_BAR __builtin_amdgcn_s_barrier()
; #define PG8_SCHED __builtin_amdgcn_sched_barrier(0)
; template <class Epi, class Sched, bool ALIGN_EPI = false, bool SP2 = false>
; __device__ __forceinline__ void gemm_phase(PG8_LAS unsigned char* lds, const Gemm g, const Sched& S, const Epi& E) {
;     ...
;             PG8_LDB(B0, 0, 0); PG8_LDB(B1, 0, 1); PG8_SCHED; PG8_LDA(At, 0, 0); PG8_STAGE(PG8_SA(1, 1), a1 + hstepA, voffA);
;             PG8_WAIT_V(8); PG8_WAIT_L(0); PG8_BAR; PG8_MMA(0, 0, At, B0); PG8_MMA(0, 1, At, B1); PG8_BAR; PG8_SCHED;
;             PG8_LDA(At, 0, 1); PG8_STAGE(PG8_SB(0, 0), b2, voffB); PG8_STAGE(PG8_SB(0, 1), b2 + hstepB, voffB); PG8_STAGE(PG8_SA(0, 0), a2, voffA);
;             PG8_WAIT_V(8); PG8_WAIT_L(0); PG8_BAR; PG8_MMA(1, 0, At, B0); PG8_MMA(1, 1, At, B1); PG8_BAR; PG8_SCHED;
.LBB0_1421:
	ds_read_b128 v[142:145], v191
	ds_read_b128 v[146:149], v191 offset:1024
	ds_read_b128 v[150:153], v191 offset:2048
	ds_read_b128 v[154:157], v191 offset:3072
	ds_read_b128 v[158:161], v192
	ds_read_b128 v[162:165], v192 offset:1024
	ds_read_b128 v[166:169], v192 offset:2048
	ds_read_b128 v[170:173], v192 offset:3072
	s_add_i32 s79, s42, 2
	s_add_u32 s43, s40, 0x4000
	s_addc_u32 s44, s41, 0
	s_cmp_eq_u32 s35, s42
	s_cselect_b32 s46, s36, s43
	s_cselect_b32 s47, s37, s44
	s_cselect_b32 s44, s38, s77
	s_cselect_b32 s45, s39, s78
	s_add_u32 s42, s46, 0x8000
	s_addc_u32 s43, s47, 0
	s_add_i32 m0, s10, 0xc000
	ds_read_b128 v[174:177], v193
	ds_read_b128 v[178:181], v193 offset:1024
	ds_read_b128 v[182:185], v193 offset:2048
	ds_read_b128 v[194:197], v193 offset:3072
	ds_read_b128 v[198:201], v193 offset:4096
	ds_read_b128 v[202:205], v193 offset:5120
	ds_read_b128 v[206:209], v193 offset:6144
	ds_read_b128 v[210:213], v193 offset:7168
	global_load_lds_dwordx4 v134, s[40:41]
	s_add_i32 m0, s10, 0xe000
	s_nop 0
	global_load_lds_dwordx4 v136, s[40:41]
	s_waitcnt vmcnt(8)
	s_waitcnt lgkmcnt(0)
	s_setprio 1
	s_barrier
	v_mfma_f32_16x16x32_bf16 v[124:127], v[142:145], v[174:177], v[124:127]
	v_mfma_f32_16x16x32_bf16 v[120:123], v[150:153], v[174:177], v[120:123]
	v_mfma_f32_16x16x32_bf16 v[108:111], v[142:145], v[182:185], v[108:111]
	v_mfma_f32_16x16x32_bf16 v[104:107], v[150:153], v[182:185], v[104:107]
	v_mfma_f32_16x16x32_bf16 v[92:95], v[142:145], v[198:201], v[92:95]
	v_mfma_f32_16x16x32_bf16 v[88:91], v[150:153], v[198:201], v[88:91]
	v_mfma_f32_16x16x32_bf16 v[76:79], v[142:145], v[206:209], v[76:79]
	v_mfma_f32_16x16x32_bf16 v[72:75], v[150:153], v[206:209], v[72:75]
	v_mfma_f32_16x16x32_bf16 v[124:127], v[146:149], v[178:181], v[124:127]
	v_mfma_f32_16x16x32_bf16 v[120:123], v[154:157], v[178:181], v[120:123]
	v_mfma_f32_16x16x32_bf16 v[108:111], v[146:149], v[194:197], v[108:111]
	v_mfma_f32_16x16x32_bf16 v[104:107], v[154:157], v[194:197], v[104:107]
	v_mfma_f32_16x16x32_bf16 v[92:95], v[146:149], v[202:205], v[92:95]
	v_mfma_f32_16x16x32_bf16 v[88:91], v[154:157], v[202:205], v[88:91]
	v_mfma_f32_16x16x32_bf16 v[76:79], v[146:149], v[210:213], v[76:79]
	v_mfma_f32_16x16x32_bf16 v[72:75], v[154:157], v[210:213], v[72:75]
	v_mfma_f32_16x16x32_bf16 v[116:119], v[158:161], v[174:177], v[116:119]
	v_mfma_f32_16x16x32_bf16 v[112:115], v[166:169], v[174:177], v[112:115]
	v_mfma_f32_16x16x32_bf16 v[100:103], v[158:161], v[182:185], v[100:103]
	v_mfma_f32_16x16x32_bf16 v[96:99], v[166:169], v[182:185], v[96:99]
	v_mfma_f32_16x16x32_bf16 v[84:87], v[158:161], v[198:201], v[84:87]
	v_mfma_f32_16x16x32_bf16 v[80:83], v[166:169], v[198:201], v[80:83]
	v_mfma_f32_16x16x32_bf16 v[68:71], v[158:161], v[206:209], v[68:71]
	v_mfma_f32_16x16x32_bf16 v[64:67], v[166:169], v[206:209], v[64:67]
	v_mfma_f32_16x16x32_bf16 v[116:119], v[162:165], v[178:181], v[116:119]
	v_mfma_f32_16x16x32_bf16 v[112:115], v[170:173], v[178:181], v[112:115]
	v_mfma_f32_16x16x32_bf16 v[100:103], v[162:165], v[194:197], v[100:103]
	v_mfma_f32_16x16x32_bf16 v[96:99], v[170:173], v[194:197], v[96:99]
	v_mfma_f32_16x16x32_bf16 v[84:87], v[162:165], v[202:205], v[84:87]
	v_mfma_f32_16x16x32_bf16 v[80:83], v[170:173], v[202:205], v[80:83]
	v_mfma_f32_16x16x32_bf16 v[68:71], v[162:165], v[210:213], v[68:71]
	v_mfma_f32_16x16x32_bf16 v[64:67], v[170:173], v[210:213], v[64:67]
	s_barrier
	s_setprio 0
	s_add_i32 s80, s52, s2
	s_mov_b32 m0, s80
	ds_read_b128 v[174:177], v193 offset:16384
	ds_read_b128 v[178:181], v193 offset:17408
	ds_read_b128 v[182:185], v193 offset:18432
	ds_read_b128 v[194:197], v193 offset:19456
	ds_read_b128 v[198:201], v193 offset:20480
	ds_read_b128 v[202:205], v193 offset:21504
	ds_read_b128 v[206:209], v193 offset:22528
	ds_read_b128 v[210:213], v193 offset:23552
	global_load_lds_dwordx4 v128, s[44:45]
	s_add_i32 m0, s80, 0x2000
	s_add_u32 s80, s44, 0x4000
	s_addc_u32 s81, s45, 0
	s_add_i32 s82, s53, s2
	global_load_lds_dwordx4 v130, s[44:45]
	s_mov_b32 m0, s82
	s_nop 0
	global_load_lds_dwordx4 v128, s[80:81]
	s_add_i32 m0, s82, 0x2000
	s_nop 0
	global_load_lds_dwordx4 v130, s[80:81]
	s_waitcnt vmcnt(6)
	s_waitcnt lgkmcnt(0)
	s_setprio 1
	s_barrier
	v_mfma_f32_16x16x32_bf16 v[60:63], v[142:145], v[174:177], v[60:63]
	v_mfma_f32_16x16x32_bf16 v[56:59], v[150:153], v[174:177], v[56:59]
	v_mfma_f32_16x16x32_bf16 v[44:47], v[142:145], v[182:185], v[44:47]
	v_mfma_f32_16x16x32_bf16 v[40:43], v[150:153], v[182:185], v[40:43]
	v_mfma_f32_16x16x32_bf16 v[28:31], v[142:145], v[198:201], v[28:31]
	v_mfma_f32_16x16x32_bf16 v[24:27], v[150:153], v[198:201], v[24:27]
	v_mfma_f32_16x16x32_bf16 v[12:15], v[142:145], v[206:209], v[12:15]
	v_mfma_f32_16x16x32_bf16 v[8:11], v[150:153], v[206:209], v[8:11]
	v_mfma_f32_16x16x32_bf16 v[60:63], v[146:149], v[178:181], v[60:63]
	v_mfma_f32_16x16x32_bf16 v[56:59], v[154:157], v[178:181], v[56:59]
	v_mfma_f32_16x16x32_bf16 v[44:47], v[146:149], v[194:197], v[44:47]
	v_mfma_f32_16x16x32_bf16 v[40:43], v[154:157], v[194:197], v[40:43]
	v_mfma_f32_16x16x32_bf16 v[28:31], v[146:149], v[202:205], v[28:31]
	v_mfma_f32_16x16x32_bf16 v[24:27], v[154:157], v[202:205], v[24:27]
	v_mfma_f32_16x16x32_bf16 v[12:15], v[146:149], v[210:213], v[12:15]
	v_mfma_f32_16x16x32_bf16 v[8:11], v[154:157], v[210:213], v[8:11]
	v_mfma_f32_16x16x32_bf16 v[52:55], v[158:161], v[174:177], v[52:55]
	v_mfma_f32_16x16x32_bf16 v[48:51], v[166:169], v[174:177], v[48:51]
	v_mfma_f32_16x16x32_bf16 v[36:39], v[158:161], v[182:185], v[36:39]
	v_mfma_f32_16x16x32_bf16 v[32:35], v[166:169], v[182:185], v[32:35]
	v_mfma_f32_16x16x32_bf16 v[20:23], v[158:161], v[198:201], v[20:23]
	v_mfma_f32_16x16x32_bf16 v[16:19], v[166:169], v[198:201], v[16:19]
	v_mfma_f32_16x16x32_bf16 v[4:7], v[158:161], v[206:209], v[4:7]
	v_mfma_f32_16x16x32_bf16 v[0:3], v[166:169], v[206:209], v[0:3]
	v_mfma_f32_16x16x32_bf16 v[52:55], v[162:165], v[178:181], v[52:55]
	v_mfma_f32_16x16x32_bf16 v[48:51], v[170:173], v[178:181], v[48:51]
	v_mfma_f32_16x16x32_bf16 v[36:39], v[162:165], v[194:197], v[36:39]
	v_mfma_f32_16x16x32_bf16 v[32:35], v[170:173], v[194:197], v[32:35]
	v_mfma_f32_16x16x32_bf16 v[20:23], v[162:165], v[202:205], v[20:23]
	v_mfma_f32_16x16x32_bf16 v[16:19], v[170:173], v[202:205], v[16:19]
	v_mfma_f32_16x16x32_bf16 v[4:7], v[162:165], v[210:213], v[4:7]
	v_mfma_f32_16x16x32_bf16 v[0:3], v[170:173], v[210:213], v[0:3]
	s_barrier
; #define PG8_STAGE(bufoff, gbase, voff) do { _Pragma("unroll") for (int _i = 0; _i < 2; ++_i) \
;         __builtin_amdgcn_global_load_lds((const unsigned*)((const char*)(gbase) + (voff)[_i]), (PG8_LAS unsigned*)(lds + (bufoff) + ldsw + _i * 8192), 16, 0, 0); } while (0)
; #define PG8_LDA(dst, b, h) do { _Pragma("unroll") for (int m = 0; m < 4; ++m) _Pragma("unroll") for (int k = 0; k < 2; ++k) dst[m][k] = *(const PG8_LAS bf16x8*)(lds + PG8_SA(b, h) + aoff + m * 2048 + k * 1024); } while (0)
; #define PG8_LDB(dst, b, h) do { _Pragma("unroll") for (int n = 0; n < 2; ++n) _Pragma("unroll") for (int k = 0; k < 2; ++k) dst[n][k] = *(const PG8_LAS bf16x8*)(lds + PG8_SB(b, h) + boff + n * 2048 + k * 1024); } while (0)
; #define PG8_MMA(ai, bj, At, Bt) do { __builtin_amdgcn_s_setprio(1); _Pragma("unroll") for (int m = 0; m < 4; ++m) _Pragma("unroll") for (int n = 0; n < 2; ++n) _Pragma("unroll") for (int k = 0; k < 2; ++k) \
;         acc[ai][bj][m][n] = __builtin_amdgcn_mfma_f32_16x16x32_bf16(Bt[n][k], At[m][k], acc[ai][bj][m][n], 0, 0, 0); __builtin_amdgcn_s_setprio(0); } while (0)
; #define PG8_WAIT_V(n) asm volatile("s_waitcnt vmcnt(" #n ")" ::: "memory")
; #define PG8_WAIT_L(n) asm volatile("s_waitcnt lgkmcnt(" #n ")" ::: "memory")
; #define PG8_BAR __builtin_amdgcn_s_barrier()
; template <class Epi, class Sched, bool ALIGN_EPI = false, bool SP2 = false>
; __device__ __forceinline__ void gemm_phase(PG8_LAS unsigned char* lds, const Gemm g, const Sched& S, const Epi& E) {
;     ...
;         for (int t = 0; t < nt; t += 2) {
;             const bool last = (t == nt - 2);
;             const char* a1 = cA + (size_t)(t + 1) * kstepA;
;             const char* a2 = last ? nA : cA + (size_t)(t + 2) * kstepA; const char* b2 = last ? nB : cB + (size_t)(t + 2) * kstepB;
;             const char* a3 = a2 + kstepA; const char* b3 = b2 + kstepB;
;     ...
;             PG8_LDB(B0, 1, 0); PG8_LDB(B1, 1, 1); PG8_SCHED; PG8_LDA(At, 1, 0); PG8_STAGE(PG8_SA(0, 1), a2 + hstepA, voffA);
;             PG8_WAIT_V(8); PG8_WAIT_L(0); PG8_BAR; PG8_MMA(0, 0, At, B0); PG8_MMA(0, 1, At, B1); PG8_BAR; PG8_SCHED;
;             PG8_LDA(At, 1, 1); PG8_STAGE(PG8_SB(1, 0), b3, voffB); PG8_STAGE(PG8_SB(1, 1), b3 + hstepB, voffB); PG8_STAGE(PG8_SA(1, 0), a3, voffA);
;             PG8_WAIT_V(8); PG8_WAIT_L(0); PG8_BAR; PG8_MMA(1, 0, At, B0); PG8_MMA(1, 1, At, B1); PG8_BAR; PG8_SCHED;
	s_setprio 0
	s_add_i32 s80, 0, 0x18000
	v_add_u32_e32 v132, s80, v189
	s_add_i32 s81, 0, 0x1c000
	ds_read_b128 v[142:145], v132
	ds_read_b128 v[146:149], v132 offset:1024
	ds_read_b128 v[150:153], v132 offset:2048
	ds_read_b128 v[154:157], v132 offset:3072
	v_add_u32_e32 v132, s81, v189
	ds_read_b128 v[158:161], v132
	ds_read_b128 v[162:165], v132 offset:1024
	ds_read_b128 v[166:169], v132 offset:2048
	ds_read_b128 v[170:173], v132 offset:3072
	s_mov_b32 m0, s10
	s_nop 0
	global_load_lds_dwordx4 v128, s[46:47]
	s_mov_b32 m0, s14
	s_nop 0
	global_load_lds_dwordx4 v130, s[46:47]
	s_add_u32 s46, s46, 0x4000
	s_addc_u32 s47, s47, 0
	s_mov_b32 m0, s15
	ds_read_b128 v[174:177], v193 offset:32768
	ds_read_b128 v[178:181], v193 offset:33792
	ds_read_b128 v[182:185], v193 offset:34816
	ds_read_b128 v[194:197], v193 offset:35840
	ds_read_b128 v[198:201], v193 offset:36864
	ds_read_b128 v[202:205], v193 offset:37888
	ds_read_b128 v[206:209], v193 offset:38912
	ds_read_b128 v[210:213], v193 offset:39936
	global_load_lds_dwordx4 v128, s[46:47]
	s_mov_b32 m0, s48
	s_nop 0
	global_load_lds_dwordx4 v130, s[46:47]
	s_waitcnt vmcnt(8)
	s_waitcnt lgkmcnt(0)
	s_setprio 1
	s_barrier
	v_mfma_f32_16x16x32_bf16 v[124:127], v[142:145], v[174:177], v[124:127]
	v_mfma_f32_16x16x32_bf16 v[120:123], v[150:153], v[174:177], v[120:123]
	v_mfma_f32_16x16x32_bf16 v[108:111], v[142:145], v[182:185], v[108:111]
	v_mfma_f32_16x16x32_bf16 v[104:107], v[150:153], v[182:185], v[104:107]
	v_mfma_f32_16x16x32_bf16 v[92:95], v[142:145], v[198:201], v[92:95]
	v_mfma_f32_16x16x32_bf16 v[88:91], v[150:153], v[198:201], v[88:91]
	v_mfma_f32_16x16x32_bf16 v[76:79], v[142:145], v[206:209], v[76:79]
	v_mfma_f32_16x16x32_bf16 v[72:75], v[150:153], v[206:209], v[72:75]
	v_mfma_f32_16x16x32_bf16 v[124:127], v[146:149], v[178:181], v[124:127]
	v_mfma_f32_16x16x32_bf16 v[120:123], v[154:157], v[178:181], v[120:123]
	v_mfma_f32_16x16x32_bf16 v[108:111], v[146:149], v[194:197], v[108:111]
	v_mfma_f32_16x16x32_bf16 v[104:107], v[154:157], v[194:197], v[104:107]
	v_mfma_f32_16x16x32_bf16 v[92:95], v[146:149], v[202:205], v[92:95]
	v_mfma_f32_16x16x32_bf16 v[88:91], v[154:157], v[202:205], v[88:91]
	v_mfma_f32_16x16x32_bf16 v[76:79], v[146:149], v[210:213], v[76:79]
	v_mfma_f32_16x16x32_bf16 v[72:75], v[154:157], v[210:213], v[72:75]
	v_mfma_f32_16x16x32_bf16 v[116:119], v[158:161], v[174:177], v[116:119]
	v_mfma_f32_16x16x32_bf16 v[112:115], v[166:169], v[174:177], v[112:115]
	v_mfma_f32_16x16x32_bf16 v[100:103], v[158:161], v[182:185], v[100:103]
	v_mfma_f32_16x16x32_bf16 v[96:99], v[166:169], v[182:185], v[96:99]
	v_mfma_f32_16x16x32_bf16 v[84:87], v[158:161], v[198:201], v[84:87]
	v_mfma_f32_16x16x32_bf16 v[80:83], v[166:169], v[198:201], v[80:83]
	v_mfma_f32_16x16x32_bf16 v[68:71], v[158:161], v[206:209], v[68:71]
	v_mfma_f32_16x16x32_bf16 v[64:67], v[166:169], v[206:209], v[64:67]
	v_mfma_f32_16x16x32_bf16 v[116:119], v[162:165], v[178:181], v[116:119]
	v_mfma_f32_16x16x32_bf16 v[112:115], v[170:173], v[178:181], v[112:115]
	v_mfma_f32_16x16x32_bf16 v[100:103], v[162:165], v[194:197], v[100:103]
	v_mfma_f32_16x16x32_bf16 v[96:99], v[170:173], v[194:197], v[96:99]
	v_mfma_f32_16x16x32_bf16 v[84:87], v[162:165], v[202:205], v[84:87]
	v_mfma_f32_16x16x32_bf16 v[80:83], v[170:173], v[202:205], v[80:83]
	v_mfma_f32_16x16x32_bf16 v[68:71], v[162:165], v[210:213], v[68:71]
	v_mfma_f32_16x16x32_bf16 v[64:67], v[170:173], v[210:213], v[64:67]
	s_barrier
	s_setprio 0
	s_add_u32 s46, s44, 0x8000
	s_addc_u32 s47, s45, 0
	s_add_i32 s80, s80, s2
	s_mov_b32 m0, s80
	ds_read_b128 v[174:177], v193 offset:49152
	ds_read_b128 v[178:181], v193 offset:50176
	ds_read_b128 v[182:185], v193 offset:51200
	ds_read_b128 v[194:197], v193 offset:52224
	ds_read_b128 v[198:201], v193 offset:53248
	ds_read_b128 v[202:205], v193 offset:54272
	ds_read_b128 v[206:209], v193 offset:55296
	ds_read_b128 v[210:213], v193 offset:56320
	global_load_lds_dwordx4 v128, s[46:47]
	s_add_i32 m0, s80, 0x2000
	s_add_u32 s44, s44, 0xc000
	s_addc_u32 s45, s45, 0
	global_load_lds_dwordx4 v130, s[46:47]
	s_add_i32 s46, s81, s2
	s_mov_b32 m0, s46
	s_nop 0
	global_load_lds_dwordx4 v128, s[44:45]
	s_add_i32 m0, s46, 0x2000
	s_nop 0
	global_load_lds_dwordx4 v130, s[44:45]
	s_mov_b32 m0, s50
	s_nop 0
	global_load_lds_dwordx4 v128, s[42:43]
	s_mov_b32 m0, s51
	s_nop 0
	global_load_lds_dwordx4 v130, s[42:43]
	s_waitcnt vmcnt(8)
	s_waitcnt lgkmcnt(0)
	s_setprio 1
	s_barrier
	v_mfma_f32_16x16x32_bf16 v[60:63], v[142:145], v[174:177], v[60:63]
	v_mfma_f32_16x16x32_bf16 v[56:59], v[150:153], v[174:177], v[56:59]
	v_mfma_f32_16x16x32_bf16 v[44:47], v[142:145], v[182:185], v[44:47]
	v_mfma_f32_16x16x32_bf16 v[40:43], v[150:153], v[182:185], v[40:43]
	v_mfma_f32_16x16x32_bf16 v[28:31], v[142:145], v[198:201], v[28:31]
	v_mfma_f32_16x16x32_bf16 v[24:27], v[150:153], v[198:201], v[24:27]
	v_mfma_f32_16x16x32_bf16 v[12:15], v[142:145], v[206:209], v[12:15]
	v_mfma_f32_16x16x32_bf16 v[8:11], v[150:153], v[206:209], v[8:11]
	v_mfma_f32_16x16x32_bf16 v[60:63], v[146:149], v[178:181], v[60:63]
	v_mfma_f32_16x16x32_bf16 v[56:59], v[154:157], v[178:181], v[56:59]
	v_mfma_f32_16x16x32_bf16 v[44:47], v[146:149], v[194:197], v[44:47]
	v_mfma_f32_16x16x32_bf16 v[40:43], v[154:157], v[194:197], v[40:43]
	v_mfma_f32_16x16x32_bf16 v[28:31], v[146:149], v[202:205], v[28:31]
	v_mfma_f32_16x16x32_bf16 v[24:27], v[154:157], v[202:205], v[24:27]
	v_mfma_f32_16x16x32_bf16 v[12:15], v[146:149], v[210:213], v[12:15]
	v_mfma_f32_16x16x32_bf16 v[8:11], v[154:157], v[210:213], v[8:11]
	v_mfma_f32_16x16x32_bf16 v[52:55], v[158:161], v[174:177], v[52:55]
	v_mfma_f32_16x16x32_bf16 v[48:51], v[166:169], v[174:177], v[48:51]
	v_mfma_f32_16x16x32_bf16 v[36:39], v[158:161], v[182:185], v[36:39]
	v_mfma_f32_16x16x32_bf16 v[32:35], v[166:169], v[182:185], v[32:35]
	v_mfma_f32_16x16x32_bf16 v[20:23], v[158:161], v[198:201], v[20:23]
	v_mfma_f32_16x16x32_bf16 v[16:19], v[166:169], v[198:201], v[16:19]
	v_mfma_f32_16x16x32_bf16 v[4:7], v[158:161], v[206:209], v[4:7]
	v_mfma_f32_16x16x32_bf16 v[0:3], v[166:169], v[206:209], v[0:3]
	v_mfma_f32_16x16x32_bf16 v[52:55], v[162:165], v[178:181], v[52:55]
	v_mfma_f32_16x16x32_bf16 v[48:51], v[170:173], v[178:181], v[48:51]
	v_mfma_f32_16x16x32_bf16 v[36:39], v[162:165], v[194:197], v[36:39]
	v_mfma_f32_16x16x32_bf16 v[32:35], v[170:173], v[194:197], v[32:35]
	v_mfma_f32_16x16x32_bf16 v[20:23], v[162:165], v[202:205], v[20:23]
	v_mfma_f32_16x16x32_bf16 v[16:19], v[170:173], v[202:205], v[16:19]
	v_mfma_f32_16x16x32_bf16 v[4:7], v[162:165], v[210:213], v[4:7]
	v_mfma_f32_16x16x32_bf16 v[0:3], v[170:173], v[210:213], v[0:3]
	s_barrier
	s_setprio 0
	s_add_u32 s40, s40, 0x10000
	s_addc_u32 s41, s41, 0
	s_add_u32 s77, s77, 0x10000
	s_addc_u32 s78, s78, 0
	s_cmp_ge_i32 s79, s76
	s_mov_b32 s42, s79
	s_cbranch_scc0 .LBB0_1421
	s_and_b64 vcc, exec, s[20:21]
	s_cbranch_vccnz .LBB0_1426
	s_mov_b64 s[40:41], -1
	s_cmp_gt_i32 s16, -1
	v_lshl_or_b32 v142, s75, 8, v190
	s_cbranch_scc1 .LBB0_1427

; __global__ void __launch_bounds__(NWAVES * 64, 2) fwd_megakernel(Args args) {
	.amdhsa_kernel _Z14fwd_megakernel4Args
		.amdhsa_group_segment_fixed_size 0
		.amdhsa_private_segment_fixed_size 0
		.amdhsa_kernarg_size 448
		.amdhsa_user_sgpr_count 2
		.amdhsa_user_sgpr_dispatch_ptr 0
		.amdhsa_user_sgpr_queue_ptr 0
		.amdhsa_user_sgpr_kernarg_segment_ptr 1
		.amdhsa_user_sgpr_dispatch_id 0
		.amdhsa_user_sgpr_kernarg_preload_length 0
		.amdhsa_user_sgpr_kernarg_preload_offset 0
		.amdhsa_user_sgpr_private_segment_size 0
		.amdhsa_uses_dynamic_stack 0
		.amdhsa_enable_private_segment 0
		.amdhsa_system_sgpr_workgroup_id_x 1
		.amdhsa_system_sgpr_workgroup_id_y 0
		.amdhsa_system_sgpr_workgroup_id_z 0
		.amdhsa_system_sgpr_workgroup_info 0
		.amdhsa_system_vgpr_workitem_id 2
		.amdhsa_next_free_vgpr 252
		.amdhsa_next_free_sgpr 102
		.amdhsa_accum_offset 252
		.amdhsa_reserve_vcc 1
		.amdhsa_float_round_mode_32 0
		.amdhsa_float_round_mode_16_64 0
		.amdhsa_float_denorm_mode_32 3
		.amdhsa_float_denorm_mode_16_64 3
		.amdhsa_dx10_clamp 1
		.amdhsa_ieee_mode 1
		.amdhsa_fp16_overflow 0
		.amdhsa_tg_split 0
		.amdhsa_exception_fp_ieee_invalid_op 0
		.amdhsa_exception_fp_denorm_src 0
		.amdhsa_exception_fp_ieee_div_zero 0
		.amdhsa_exception_fp_ieee_overflow 0
		.amdhsa_exception_fp_ieee_underflow 0
		.amdhsa_exception_fp_ieee_inexact 0
		.amdhsa_exception_int_div_zero 0
	.end_amdhsa_kernel

; __global__ void __launch_bounds__(NWAVES * 64, 2) fwd_megakernel(Args args) {
amdhsa.kernels:
  - .agpr_count:     0
    .args:
      - .offset:         0
        .size:           192
        .value_kind:     by_value
      - .offset:         192
        .size:           4
        .value_kind:     hidden_block_count_x
      - .offset:         196
        .size:           4
        .value_kind:     hidden_block_count_y
      - .offset:         200
        .size:           4
        .value_kind:     hidden_block_count_z
      - .offset:         204
        .size:           2
        .value_kind:     hidden_group_size_x
      - .offset:         206
        .size:           2
        .value_kind:     hidden_group_size_y
      - .offset:         208
        .size:           2
        .value_kind:     hidden_group_size_z
      - .offset:         210
        .size:           2
        .value_kind:     hidden_remainder_x
      - .offset:         212
        .size:           2
        .value_kind:     hidden_remainder_y
      - .offset:         214
        .size:           2
        .value_kind:     hidden_remainder_z
      - .offset:         232
        .size:           8
        .value_kind:     hidden_global_offset_x
      - .offset:         240
        .size:           8
        .value_kind:     hidden_global_offset_y
      - .offset:         248
        .size:           8
        .value_kind:     hidden_global_offset_z
      - .offset:         256
        .size:           2
        .value_kind:     hidden_grid_dims
      - .offset:         280
        .size:           8
        .value_kind:     hidden_multigrid_sync_arg
      - .offset:         312
        .size:           4
        .value_kind:     hidden_dynamic_lds_size
    .group_segment_fixed_size: 0
    .kernarg_segment_align: 8
    .kernarg_segment_size: 448
    .language:       OpenCL C
    .language_version:
      - 2
      - 0
    .max_flat_workgroup_size: 512
    .name:           _Z14fwd_megakernel4Args
    .private_segment_fixed_size: 0
    .sgpr_count:     108
    .sgpr_spill_count: 116
    .symbol:         _Z14fwd_megakernel4Args.kd
    .uniform_work_group_size: 1
    .uses_dynamic_stack: false
    .vgpr_count:     252
    .vgpr_spill_count: 0
    .wavefront_size: 64
